# v_combo8 + top-k score MFMAs fed by a rolling pipeline of sub-key fragment reads (three 16-key blocks in flight)
# baseline (speedup 1.0000x reference)
.LBB0_1346:
	s_mov_b32 s78, 0x10001
	s_mov_b32 s79, 0x10001
	v_mov_b32_e32 v134, 0
	v_mov_b32_e32 v135, 0
	v_add_co_u32_e32 v2, vcc, 0xe000, v0
	s_mov_b32 s40, 0
	s_nop 0
	v_addc_co_u32_e32 v3, vcc, 0, v1, vcc
	v_add_co_u32_e32 v4, vcc, 0xc000, v0
	s_mov_b64 s[0:1], vcc
	v_add_co_u32_e32 v6, vcc, 0xa000, v0
	s_nop 1
	v_addc_co_u32_e32 v7, vcc, 0, v1, vcc
	v_add_co_u32_e32 v8, vcc, 0x8000, v0
	s_nop 1
	v_addc_co_u32_e32 v9, vcc, 0, v1, vcc
	v_add_co_u32_e32 v10, vcc, 0x6000, v0
	s_nop 1
	v_addc_co_u32_e32 v11, vcc, 0, v1, vcc
	v_add_co_u32_e32 v14, vcc, 0x4000, v0
	s_nop 1
	v_addc_co_u32_e32 v15, vcc, 0, v1, vcc
	v_add_co_u32_e32 v18, vcc, 0x2000, v0
	s_nop 1
	v_addc_co_u32_e32 v19, vcc, 0, v1, vcc
	global_load_dwordx4 v[18:21], v[18:19], off
	s_nop 0
	global_load_dwordx4 v[22:25], v[0:1], off
	global_load_dwordx4 v[26:29], v[10:11], off
	global_load_dwordx4 v[30:33], v[14:15], off
	global_load_dwordx4 v[34:37], v[6:7], off
	global_load_dwordx4 v[38:41], v[8:9], off
	v_addc_co_u32_e64 v5, vcc, 0, v1, s[0:1]
	global_load_dwordx4 v[42:45], v[4:5], off
	global_load_dwordx4 v[46:49], v[2:3], off
	global_load_dwordx4 v[50:53], v[12:13], off
	global_load_dwordx4 v[54:57], v[12:13], off offset:64
	global_load_dwordx4 v[58:61], v[12:13], off offset:128
	global_load_dwordx4 v[62:65], v[12:13], off offset:192
	s_nop 0
	global_load_dwordx4 v[0:3], v[12:13], off offset:448
	global_load_dwordx4 v[4:7], v[12:13], off offset:384
	global_load_dwordx4 v[8:11], v[12:13], off offset:320
	s_nop 0
	global_load_dwordx4 v[12:15], v[12:13], off offset:256
	s_waitcnt lgkmcnt(0)
	s_barrier
	s_waitcnt vmcnt(14)
	ds_write_b128 v208, v[22:25]
	ds_write_b128 v209, v[18:21]
	s_waitcnt vmcnt(12)
	ds_write_b128 v210, v[30:33]
	ds_write_b128 v211, v[26:29]
	s_waitcnt vmcnt(10)
	ds_write_b128 v212, v[38:41]
	ds_write_b128 v213, v[34:37]
	s_waitcnt vmcnt(9)
	ds_write_b128 v214, v[42:45]
	s_waitcnt vmcnt(8)
	ds_write_b128 v215, v[46:49]
	s_waitcnt lgkmcnt(0)
	s_barrier
	ds_read_b128 v[70:73], v184
	ds_read_b128 v[74:77], v184 offset:64
	ds_read_b128 v[78:81], v184 offset:128
	ds_read_b128 v[82:85], v184 offset:192
	ds_read_b128 v[86:89], v184 offset:4352
	ds_read_b128 v[90:93], v184 offset:4416
	ds_read_b128 v[94:97], v184 offset:4480
	ds_read_b128 v[98:101], v184 offset:4544
	ds_read_b128 v[102:105], v184 offset:8704
	ds_read_b128 v[106:109], v184 offset:8768
	ds_read_b128 v[110:113], v184 offset:8832
	ds_read_b128 v[114:117], v184 offset:8896
	s_waitcnt vmcnt(4)
	s_waitcnt lgkmcnt(8)
	v_mfma_f32_16x16x32_bf16 v[18:21], v[50:53], v[70:73], 0
	v_mfma_f32_16x16x32_bf16 v[18:21], v[54:57], v[74:77], v[18:21]
	v_mfma_f32_16x16x32_bf16 v[18:21], v[58:61], v[78:81], v[18:21]
	v_mfma_f32_16x16x32_bf16 v[18:21], v[62:65], v[82:85], v[18:21]
	ds_read_b128 v[118:121], v184 offset:13056
	ds_read_b128 v[122:125], v184 offset:13120
	ds_read_b128 v[126:129], v184 offset:13184
	ds_read_b128 v[130:133], v184 offset:13248
	s_waitcnt lgkmcnt(8)
	v_mfma_f32_16x16x32_bf16 v[22:25], v[50:53], v[86:89], 0
	v_mfma_f32_16x16x32_bf16 v[22:25], v[54:57], v[90:93], v[22:25]
	v_mfma_f32_16x16x32_bf16 v[22:25], v[58:61], v[94:97], v[22:25]
	v_mfma_f32_16x16x32_bf16 v[22:25], v[62:65], v[98:101], v[22:25]
	ds_read_b128 v[70:73], v184 offset:17408
	ds_read_b128 v[74:77], v184 offset:17472
	ds_read_b128 v[78:81], v184 offset:17536
	ds_read_b128 v[82:85], v184 offset:17600
	s_waitcnt lgkmcnt(8)
	v_mfma_f32_16x16x32_bf16 v[26:29], v[50:53], v[102:105], 0
	v_mfma_f32_16x16x32_bf16 v[26:29], v[54:57], v[106:109], v[26:29]
	v_mfma_f32_16x16x32_bf16 v[26:29], v[58:61], v[110:113], v[26:29]
	v_mfma_f32_16x16x32_bf16 v[26:29], v[62:65], v[114:117], v[26:29]
	ds_read_b128 v[86:89], v184 offset:21760
	ds_read_b128 v[90:93], v184 offset:21824
	ds_read_b128 v[94:97], v184 offset:21888
	ds_read_b128 v[98:101], v184 offset:21952
	s_waitcnt lgkmcnt(8)
	v_mfma_f32_16x16x32_bf16 v[30:33], v[50:53], v[118:121], 0
	v_mfma_f32_16x16x32_bf16 v[30:33], v[54:57], v[122:125], v[30:33]
	v_mfma_f32_16x16x32_bf16 v[30:33], v[58:61], v[126:129], v[30:33]
	v_mfma_f32_16x16x32_bf16 v[30:33], v[62:65], v[130:133], v[30:33]
	ds_read_b128 v[102:105], v184 offset:26112
	ds_read_b128 v[106:109], v184 offset:26176
	ds_read_b128 v[110:113], v184 offset:26240
	ds_read_b128 v[114:117], v184 offset:26304
	s_waitcnt lgkmcnt(8)
	v_mfma_f32_16x16x32_bf16 v[34:37], v[50:53], v[70:73], 0
	v_mfma_f32_16x16x32_bf16 v[34:37], v[54:57], v[74:77], v[34:37]
	v_mfma_f32_16x16x32_bf16 v[34:37], v[58:61], v[78:81], v[34:37]
	v_mfma_f32_16x16x32_bf16 v[34:37], v[62:65], v[82:85], v[34:37]
	ds_read_b128 v[118:121], v184 offset:30464
	ds_read_b128 v[122:125], v184 offset:30528
	ds_read_b128 v[126:129], v184 offset:30592
	ds_read_b128 v[130:133], v184 offset:30656
	s_waitcnt lgkmcnt(8)
	v_mfma_f32_16x16x32_bf16 v[38:41], v[50:53], v[86:89], 0
	v_mfma_f32_16x16x32_bf16 v[38:41], v[54:57], v[90:93], v[38:41]
	v_mfma_f32_16x16x32_bf16 v[38:41], v[58:61], v[94:97], v[38:41]
	v_mfma_f32_16x16x32_bf16 v[38:41], v[62:65], v[98:101], v[38:41]
	s_waitcnt lgkmcnt(4)
	v_mfma_f32_16x16x32_bf16 v[42:45], v[50:53], v[102:105], 0
	v_mfma_f32_16x16x32_bf16 v[42:45], v[54:57], v[106:109], v[42:45]
	v_mfma_f32_16x16x32_bf16 v[42:45], v[58:61], v[110:113], v[42:45]
	v_mfma_f32_16x16x32_bf16 v[42:45], v[62:65], v[114:117], v[42:45]
	s_waitcnt lgkmcnt(0)
	v_mfma_f32_16x16x32_bf16 v[46:49], v[50:53], v[118:121], 0
	v_mfma_f32_16x16x32_bf16 v[46:49], v[54:57], v[122:125], v[46:49]
	v_mfma_f32_16x16x32_bf16 v[46:49], v[58:61], v[126:129], v[46:49]
	v_mfma_f32_16x16x32_bf16 v[46:49], v[62:65], v[130:133], v[46:49]
	s_nop 7
	s_nop 7
	s_nop 1
	v_ashrrev_i32_e32 v50, 31, v49
	v_bitop3_b32 v49, v49, v50, v217 bitop3:0x1e
	v_and_or_b32 v49, v49, s67, v178
	v_ashrrev_i32_e32 v50, 31, v45
	v_bitop3_b32 v45, v45, v50, v217 bitop3:0x1e
	v_and_or_b32 v50, v45, s67, v177
	v_ashrrev_i32_e32 v45, 31, v41
	v_bitop3_b32 v41, v41, v45, v217 bitop3:0x1e
	v_and_or_b32 v51, v41, s67, v176
	v_ashrrev_i32_e32 v41, 31, v37
	v_bitop3_b32 v37, v37, v41, v217 bitop3:0x1e
	v_and_or_b32 v52, v37, s67, v175
	v_ashrrev_i32_e32 v37, 31, v33
	v_bitop3_b32 v33, v33, v37, v217 bitop3:0x1e
	v_and_or_b32 v53, v33, s67, v170
	v_ashrrev_i32_e32 v33, 31, v29
	v_bitop3_b32 v29, v29, v33, v217 bitop3:0x1e
	v_and_or_b32 v54, v29, s67, v181
	v_ashrrev_i32_e32 v29, 31, v25
	v_bitop3_b32 v25, v25, v29, v217 bitop3:0x1e
	v_and_or_b32 v55, v25, s67, v180
	v_ashrrev_i32_e32 v25, 31, v21
	v_bitop3_b32 v21, v21, v25, v217 bitop3:0x1e
	v_and_or_b32 v21, v21, s67, v179
	v_ashrrev_i32_e32 v25, 31, v48
	v_bitop3_b32 v25, v48, v25, v217 bitop3:0x1e
	v_and_or_b32 v41, v25, s67, v178
	v_ashrrev_i32_e32 v25, 31, v44
	v_bitop3_b32 v25, v44, v25, v217 bitop3:0x1e
	v_and_or_b32 v44, v25, s67, v177
	v_ashrrev_i32_e32 v25, 31, v40
	v_bitop3_b32 v25, v40, v25, v217 bitop3:0x1e
	v_and_or_b32 v40, v25, s67, v176
	v_ashrrev_i32_e32 v25, 31, v36
	v_bitop3_b32 v25, v36, v25, v217 bitop3:0x1e
	v_and_or_b32 v45, v25, s67, v175
	v_ashrrev_i32_e32 v25, 31, v32
	v_bitop3_b32 v25, v32, v25, v217 bitop3:0x1e
	v_and_or_b32 v48, v25, s67, v170
	v_ashrrev_i32_e32 v25, 31, v28
	v_bitop3_b32 v25, v28, v25, v217 bitop3:0x1e
	v_and_or_b32 v56, v25, s67, v181
	v_ashrrev_i32_e32 v25, 31, v24
	v_bitop3_b32 v24, v24, v25, v217 bitop3:0x1e
	v_and_or_b32 v57, v24, s67, v180
	v_ashrrev_i32_e32 v24, 31, v20
	v_bitop3_b32 v20, v20, v24, v217 bitop3:0x1e
	v_and_or_b32 v20, v20, s67, v179
	v_ashrrev_i32_e32 v24, 31, v47
	v_bitop3_b32 v24, v47, v24, v217 bitop3:0x1e
	v_and_or_b32 v32, v24, s67, v178
	v_min_u32_e32 v47, v52, v51
	v_ashrrev_i32_e32 v24, 31, v43
	v_bitop3_b32 v24, v43, v24, v217 bitop3:0x1e
	v_and_or_b32 v33, v24, s67, v177
	v_ashrrev_i32_e32 v24, 31, v39
	v_bitop3_b32 v24, v39, v24, v217 bitop3:0x1e
	v_and_or_b32 v36, v24, s67, v176
	v_ashrrev_i32_e32 v24, 31, v35
	v_bitop3_b32 v24, v35, v24, v217 bitop3:0x1e
	v_and_or_b32 v35, v24, s67, v175
	v_ashrrev_i32_e32 v24, 31, v31
	v_bitop3_b32 v24, v31, v24, v217 bitop3:0x1e
	v_and_or_b32 v31, v24, s67, v170
	v_ashrrev_i32_e32 v24, 31, v27
	v_bitop3_b32 v24, v27, v24, v217 bitop3:0x1e
	v_and_or_b32 v37, v24, s67, v181
	v_ashrrev_i32_e32 v24, 31, v23
	v_bitop3_b32 v23, v23, v24, v217 bitop3:0x1e
	v_and_or_b32 v39, v23, s67, v180
	v_ashrrev_i32_e32 v23, 31, v19
	v_bitop3_b32 v19, v19, v23, v217 bitop3:0x1e
	v_and_or_b32 v19, v19, s67, v179
	v_ashrrev_i32_e32 v23, 31, v46
	v_bitop3_b32 v23, v46, v23, v217 bitop3:0x1e
	v_and_or_b32 v23, v23, s67, v178
	v_ashrrev_i32_e32 v24, 31, v42
	v_bitop3_b32 v24, v42, v24, v217 bitop3:0x1e
	v_and_or_b32 v24, v24, s67, v177
	v_ashrrev_i32_e32 v25, 31, v38
	v_bitop3_b32 v25, v38, v25, v217 bitop3:0x1e
	v_and_or_b32 v25, v25, s67, v176
	v_ashrrev_i32_e32 v27, 31, v34
	v_bitop3_b32 v27, v34, v27, v217 bitop3:0x1e
	v_and_or_b32 v27, v27, s67, v175
	v_ashrrev_i32_e32 v28, 31, v30
	v_bitop3_b32 v28, v30, v28, v217 bitop3:0x1e
	v_and_or_b32 v28, v28, s67, v170
	v_ashrrev_i32_e32 v29, 31, v26
	v_bitop3_b32 v26, v26, v29, v217 bitop3:0x1e
	v_and_or_b32 v26, v26, s67, v181
	v_ashrrev_i32_e32 v29, 31, v22
	v_bitop3_b32 v22, v22, v29, v217 bitop3:0x1e
	v_and_or_b32 v22, v22, s67, v180
	v_ashrrev_i32_e32 v29, 31, v18
	v_bitop3_b32 v18, v18, v29, v217 bitop3:0x1e
	v_and_or_b32 v18, v18, s67, v179
	v_max_u32_e32 v29, v18, v22
	v_min_u32_e32 v18, v18, v22
	v_max_u32_e32 v22, v26, v28
	v_min_u32_e32 v26, v26, v28
	v_max_u32_e32 v28, v27, v25
	v_min_u32_e32 v25, v27, v25
	v_max_u32_e32 v27, v24, v23
	v_min_u32_e32 v23, v24, v23
	v_max_u32_e32 v24, v29, v22
	v_min_u32_e32 v22, v29, v22
	v_max_u32_e32 v29, v18, v26
	v_min_u32_e32 v18, v18, v26
	v_max_u32_e32 v26, v28, v27
	v_min_u32_e32 v27, v28, v27
	v_max_u32_e32 v28, v25, v23
	v_min_u32_e32 v23, v25, v23
	v_max_u32_e32 v25, v29, v22
	v_min_u32_e32 v29, v29, v22
	v_max_u32_e32 v30, v28, v27
	v_min_u32_e32 v27, v28, v27
	v_max_u32_e32 v80, v24, v26
	v_min_u32_e32 v24, v24, v26
	v_max_u32_e32 v26, v25, v30
	v_min_u32_e32 v25, v25, v30
	v_max_u32_e32 v28, v29, v27
	v_min_u32_e32 v29, v29, v27
	v_max_u32_e32 v27, v18, v23
	v_min_u32_e32 v87, v18, v23
	v_max_u32_e32 v18, v28, v24
	v_min_u32_e32 v28, v28, v24
	v_max_u32_e32 v30, v27, v25
	v_min_u32_e32 v34, v27, v25
	v_max_u32_e32 v81, v26, v18
	v_min_u32_e32 v82, v26, v18
	v_max_u32_e32 v83, v30, v28
	v_min_u32_e32 v84, v30, v28
	v_max_u32_e32 v85, v34, v29
	v_min_u32_e32 v86, v34, v29
	v_max_u32_e32 v18, v19, v39
	v_min_u32_e32 v19, v19, v39
	v_max_u32_e32 v30, v37, v31
	v_min_u32_e32 v31, v37, v31
	v_max_u32_e32 v34, v35, v36
	v_min_u32_e32 v35, v35, v36
	v_max_u32_e32 v36, v33, v32
	v_min_u32_e32 v32, v33, v32
	v_max_u32_e32 v33, v18, v30
	v_min_u32_e32 v18, v18, v30
	v_max_u32_e32 v30, v19, v31
	v_min_u32_e32 v19, v19, v31
	v_max_u32_e32 v31, v34, v36
	v_min_u32_e32 v34, v34, v36
	v_max_u32_e32 v36, v35, v32
	v_min_u32_e32 v32, v35, v32
	v_max_u32_e32 v35, v30, v18
	v_min_u32_e32 v18, v30, v18
	v_max_u32_e32 v37, v36, v34
	v_min_u32_e32 v34, v36, v34
	v_max_u32_e32 v72, v33, v31
	v_min_u32_e32 v33, v33, v31
	v_max_u32_e32 v36, v35, v37
	v_min_u32_e32 v35, v35, v37
	v_max_u32_e32 v37, v18, v34
	v_min_u32_e32 v18, v18, v34
	v_max_u32_e32 v34, v19, v32
	v_min_u32_e32 v79, v19, v32
	v_max_u32_e32 v19, v37, v33
	v_min_u32_e32 v37, v37, v33
	v_max_u32_e32 v38, v34, v35
	v_min_u32_e32 v39, v34, v35
	v_max_u32_e32 v73, v36, v19
	v_min_u32_e32 v74, v36, v19
	v_max_u32_e32 v75, v38, v37
	v_min_u32_e32 v76, v38, v37
	v_max_u32_e32 v77, v39, v18
	v_min_u32_e32 v78, v39, v18
	v_max_u32_e32 v18, v20, v57
	v_min_u32_e32 v19, v20, v57
	v_max_u32_e32 v20, v56, v48
	v_min_u32_e32 v38, v56, v48
	v_max_u32_e32 v39, v45, v40
	v_min_u32_e32 v40, v45, v40
	v_max_u32_e32 v42, v44, v41
	v_min_u32_e32 v41, v44, v41
	v_max_u32_e32 v43, v18, v20
	v_min_u32_e32 v18, v18, v20
	v_max_u32_e32 v20, v19, v38
	v_min_u32_e32 v19, v19, v38
	v_max_u32_e32 v44, v39, v42
	v_min_u32_e32 v38, v39, v42
	v_max_u32_e32 v39, v40, v41
	v_min_u32_e32 v40, v40, v41
	v_max_u32_e32 v41, v20, v18
	v_min_u32_e32 v18, v20, v18
	v_max_u32_e32 v20, v39, v38
	v_min_u32_e32 v39, v39, v38
	v_max_u32_e32 v88, v43, v44
	v_min_u32_e32 v42, v43, v44
	v_max_u32_e32 v43, v41, v20
	v_min_u32_e32 v20, v41, v20
	v_max_u32_e32 v41, v18, v39
	v_max_u32_e32 v44, v19, v40
	v_min_u32_e32 v18, v18, v39
	v_min_u32_e32 v95, v19, v40
	v_max_u32_e32 v19, v41, v42
	v_min_u32_e32 v45, v41, v42
	v_max_u32_e32 v46, v44, v20
	v_min_u32_e32 v20, v44, v20
	v_max_u32_e32 v89, v43, v19
	v_min_u32_e32 v90, v43, v19
	v_max_u32_e32 v91, v46, v45
	v_min_u32_e32 v92, v46, v45
	v_max_u32_e32 v93, v20, v18
	v_min_u32_e32 v94, v20, v18
	v_max_u32_e32 v18, v21, v55
	v_min_u32_e32 v19, v21, v55
	v_max_u32_e32 v20, v54, v53
	v_min_u32_e32 v21, v54, v53
	v_max_u32_e32 v46, v52, v51
	v_max_u32_e32 v48, v50, v49
	v_min_u32_e32 v49, v50, v49
	v_max_u32_e32 v50, v18, v20
	v_min_u32_e32 v18, v18, v20
	v_max_u32_e32 v20, v19, v21
	v_min_u32_e32 v19, v19, v21
	v_max_u32_e32 v21, v46, v48
	v_min_u32_e32 v46, v46, v48
	v_max_u32_e32 v48, v47, v49
	v_min_u32_e32 v47, v47, v49
	v_max_u32_e32 v49, v20, v18
	v_min_u32_e32 v18, v20, v18
	v_max_u32_e32 v20, v48, v46
	v_min_u32_e32 v48, v48, v46
	v_max_u32_e32 v96, v50, v21
	v_min_u32_e32 v21, v50, v21
	v_max_u32_e32 v50, v49, v20
	v_min_u32_e32 v20, v49, v20
	v_max_u32_e32 v49, v18, v48
	v_min_u32_e32 v18, v18, v48
	v_max_u32_e32 v48, v19, v47
	v_min_u32_e32 v103, v19, v47
	v_max_u32_e32 v19, v49, v21
	v_min_u32_e32 v21, v49, v21
	v_max_u32_e32 v51, v48, v20
	v_min_u32_e32 v20, v48, v20
	v_max_u32_e32 v97, v50, v19
	v_min_u32_e32 v98, v50, v19
	v_max_u32_e32 v99, v51, v21
	v_min_u32_e32 v100, v51, v21
	v_max_u32_e32 v101, v20, v18
	v_min_u32_e32 v102, v20, v18
	v_mov_b32_e32 v18, 0
	v_mov_b32_e32 v19, 0
	v_mov_b32_e32 v20, 0
	v_mov_b32_e32 v21, 0
.LBB0_1347:
	v_max_u32_dpp v55, v72, v72 row_ror:1 row_mask:0xf bank_mask:0xf bound_ctrl:1
	v_max_u32_dpp v54, v80, v80 row_ror:1 row_mask:0xf bank_mask:0xf bound_ctrl:1
	v_max_u32_dpp v56, v88, v88 row_ror:1 row_mask:0xf bank_mask:0xf bound_ctrl:1
	v_max_u32_dpp v55, v55, v55 row_ror:2 row_mask:0xf bank_mask:0xf bound_ctrl:1
	v_max_u32_dpp v57, v96, v96 row_ror:1 row_mask:0xf bank_mask:0xf bound_ctrl:1
	v_max_u32_dpp v54, v54, v54 row_ror:2 row_mask:0xf bank_mask:0xf bound_ctrl:1
	v_max_u32_dpp v56, v56, v56 row_ror:2 row_mask:0xf bank_mask:0xf bound_ctrl:1
	v_max_u32_dpp v55, v55, v55 row_ror:4 row_mask:0xf bank_mask:0xf bound_ctrl:1
	v_max_u32_dpp v57, v57, v57 row_ror:2 row_mask:0xf bank_mask:0xf bound_ctrl:1
	v_max_u32_dpp v54, v54, v54 row_ror:4 row_mask:0xf bank_mask:0xf bound_ctrl:1
	v_max_u32_dpp v56, v56, v56 row_ror:4 row_mask:0xf bank_mask:0xf bound_ctrl:1
	v_max_u32_dpp v55, v55, v55 row_ror:8 row_mask:0xf bank_mask:0xf bound_ctrl:1
	v_max_u32_dpp v57, v57, v57 row_ror:4 row_mask:0xf bank_mask:0xf bound_ctrl:1
	v_max_u32_dpp v54, v54, v54 row_ror:8 row_mask:0xf bank_mask:0xf bound_ctrl:1
	v_max_u32_dpp v56, v56, v56 row_ror:8 row_mask:0xf bank_mask:0xf bound_ctrl:1
	v_max_u32_dpp v57, v57, v57 row_ror:8 row_mask:0xf bank_mask:0xf bound_ctrl:1
	v_cmp_eq_u32_e64 s[84:85], v72, v55
	v_cmp_eq_u32_e64 s[86:87], v80, v54
	v_cmp_eq_u32_e64 s[88:89], v88, v56
	v_cmp_eq_u32_e64 s[90:91], v96, v57
	s_mov_b64 exec, s[84:85]
	v_pk_mov_b32 v[72:73], v[72:73], v[74:75] op_sel:[1,0] op_sel_hi:[1,0]
	v_pk_mov_b32 v[74:75], v[74:75], v[76:77] op_sel:[1,0] op_sel_hi:[1,0]
	v_pk_mov_b32 v[76:77], v[76:77], v[78:79] op_sel:[1,0] op_sel_hi:[1,0]
	v_pk_mov_b32 v[78:79], v[78:79], v[134:135] op_sel:[1,0] op_sel_hi:[1,0]
	s_mov_b64 exec, s[86:87]
	v_pk_mov_b32 v[80:81], v[80:81], v[82:83] op_sel:[1,0] op_sel_hi:[1,0]
	v_pk_mov_b32 v[82:83], v[82:83], v[84:85] op_sel:[1,0] op_sel_hi:[1,0]
	v_pk_mov_b32 v[84:85], v[84:85], v[86:87] op_sel:[1,0] op_sel_hi:[1,0]
	v_pk_mov_b32 v[86:87], v[86:87], v[134:135] op_sel:[1,0] op_sel_hi:[1,0]
	s_mov_b64 exec, s[88:89]
	v_pk_mov_b32 v[88:89], v[88:89], v[90:91] op_sel:[1,0] op_sel_hi:[1,0]
	v_pk_mov_b32 v[90:91], v[90:91], v[92:93] op_sel:[1,0] op_sel_hi:[1,0]
	v_pk_mov_b32 v[92:93], v[92:93], v[94:95] op_sel:[1,0] op_sel_hi:[1,0]
	v_pk_mov_b32 v[94:95], v[94:95], v[134:135] op_sel:[1,0] op_sel_hi:[1,0]
	s_mov_b64 exec, s[90:91]
	v_pk_mov_b32 v[96:97], v[96:97], v[98:99] op_sel:[1,0] op_sel_hi:[1,0]
	v_pk_mov_b32 v[98:99], v[98:99], v[100:101] op_sel:[1,0] op_sel_hi:[1,0]
	v_pk_mov_b32 v[100:101], v[100:101], v[102:103] op_sel:[1,0] op_sel_hi:[1,0]
	v_pk_mov_b32 v[102:103], v[102:103], v[134:135] op_sel:[1,0] op_sel_hi:[1,0]
	s_lshl_b64 exec, s[78:79], s40
	s_add_i32 s40, s40, 1
	v_pk_mov_b32 v[18:19], v[54:55], v[54:55] op_sel:[0,1] op_sel_hi:[0,1]
	v_pk_mov_b32 v[20:21], v[56:57], v[56:57] op_sel:[0,1] op_sel_hi:[0,1]
	s_mov_b64 exec, -1
	s_cmp_lg_u32 s40, 8
	s_cbranch_scc1 .LBB0_1347
	v_max_u32_dpp v55, v72, v72 row_ror:1 row_mask:0xf bank_mask:0xf bound_ctrl:1
	v_max_u32_dpp v54, v80, v80 row_ror:1 row_mask:0xf bank_mask:0xf bound_ctrl:1
	v_max_u32_dpp v56, v88, v88 row_ror:1 row_mask:0xf bank_mask:0xf bound_ctrl:1
	v_max_u32_dpp v55, v55, v55 row_ror:2 row_mask:0xf bank_mask:0xf bound_ctrl:1
	v_max_u32_dpp v57, v96, v96 row_ror:1 row_mask:0xf bank_mask:0xf bound_ctrl:1
	v_max_u32_dpp v54, v54, v54 row_ror:2 row_mask:0xf bank_mask:0xf bound_ctrl:1
	v_max_u32_dpp v56, v56, v56 row_ror:2 row_mask:0xf bank_mask:0xf bound_ctrl:1
	v_max_u32_dpp v55, v55, v55 row_ror:4 row_mask:0xf bank_mask:0xf bound_ctrl:1
	v_max_u32_dpp v57, v57, v57 row_ror:2 row_mask:0xf bank_mask:0xf bound_ctrl:1
	v_max_u32_dpp v54, v54, v54 row_ror:4 row_mask:0xf bank_mask:0xf bound_ctrl:1
	v_max_u32_dpp v56, v56, v56 row_ror:4 row_mask:0xf bank_mask:0xf bound_ctrl:1
	v_max_u32_dpp v55, v55, v55 row_ror:8 row_mask:0xf bank_mask:0xf bound_ctrl:1
	v_max_u32_dpp v57, v57, v57 row_ror:4 row_mask:0xf bank_mask:0xf bound_ctrl:1
	v_max_u32_dpp v54, v54, v54 row_ror:8 row_mask:0xf bank_mask:0xf bound_ctrl:1
	v_max_u32_dpp v56, v56, v56 row_ror:8 row_mask:0xf bank_mask:0xf bound_ctrl:1
	v_max_u32_dpp v57, v57, v57 row_ror:8 row_mask:0xf bank_mask:0xf bound_ctrl:1
	v_cmp_eq_u32_e64 s[84:85], v72, v55
	v_cmp_eq_u32_e64 s[86:87], v80, v54
	v_cmp_eq_u32_e64 s[88:89], v88, v56
	v_cmp_eq_u32_e64 s[90:91], v96, v57
	s_mov_b64 exec, s[84:85]
	v_pk_mov_b32 v[72:73], v[72:73], v[74:75] op_sel:[1,0] op_sel_hi:[1,0]
	v_pk_mov_b32 v[74:75], v[74:75], v[76:77] op_sel:[1,0] op_sel_hi:[1,0]
	v_pk_mov_b32 v[76:77], v[76:77], v[78:79] op_sel:[1,0] op_sel_hi:[1,0]
	v_pk_mov_b32 v[78:79], v[78:79], v[134:135] op_sel:[1,0] op_sel_hi:[1,0]
	s_mov_b64 exec, s[86:87]
	v_pk_mov_b32 v[80:81], v[80:81], v[82:83] op_sel:[1,0] op_sel_hi:[1,0]
	v_pk_mov_b32 v[82:83], v[82:83], v[84:85] op_sel:[1,0] op_sel_hi:[1,0]
	v_pk_mov_b32 v[84:85], v[84:85], v[86:87] op_sel:[1,0] op_sel_hi:[1,0]
	v_pk_mov_b32 v[86:87], v[86:87], v[134:135] op_sel:[1,0] op_sel_hi:[1,0]
	s_mov_b64 exec, s[88:89]
	v_pk_mov_b32 v[88:89], v[88:89], v[90:91] op_sel:[1,0] op_sel_hi:[1,0]
	v_pk_mov_b32 v[90:91], v[90:91], v[92:93] op_sel:[1,0] op_sel_hi:[1,0]
	v_pk_mov_b32 v[92:93], v[92:93], v[94:95] op_sel:[1,0] op_sel_hi:[1,0]
	v_pk_mov_b32 v[94:95], v[94:95], v[134:135] op_sel:[1,0] op_sel_hi:[1,0]
	s_mov_b64 exec, s[90:91]
	v_pk_mov_b32 v[96:97], v[96:97], v[98:99] op_sel:[1,0] op_sel_hi:[1,0]
	v_pk_mov_b32 v[98:99], v[98:99], v[100:101] op_sel:[1,0] op_sel_hi:[1,0]
	v_pk_mov_b32 v[100:101], v[100:101], v[102:103] op_sel:[1,0] op_sel_hi:[1,0]
	v_pk_mov_b32 v[102:103], v[102:103], v[134:135] op_sel:[1,0] op_sel_hi:[1,0]
	s_lshl_b64 exec, s[78:79], s40
	s_add_i32 s40, s40, 1
	v_pk_mov_b32 v[18:19], v[54:55], v[54:55] op_sel:[0,1] op_sel_hi:[0,1]
	v_pk_mov_b32 v[20:21], v[56:57], v[56:57] op_sel:[0,1] op_sel_hi:[0,1]
	s_mov_b64 exec, -1
	v_max_u32_dpp v55, v72, v72 row_ror:1 row_mask:0xf bank_mask:0xf bound_ctrl:1
	v_max_u32_dpp v54, v80, v80 row_ror:1 row_mask:0xf bank_mask:0xf bound_ctrl:1
	v_max_u32_dpp v56, v88, v88 row_ror:1 row_mask:0xf bank_mask:0xf bound_ctrl:1
	v_max_u32_dpp v55, v55, v55 row_ror:2 row_mask:0xf bank_mask:0xf bound_ctrl:1
	v_max_u32_dpp v57, v96, v96 row_ror:1 row_mask:0xf bank_mask:0xf bound_ctrl:1
	v_max_u32_dpp v54, v54, v54 row_ror:2 row_mask:0xf bank_mask:0xf bound_ctrl:1
	v_max_u32_dpp v56, v56, v56 row_ror:2 row_mask:0xf bank_mask:0xf bound_ctrl:1
	v_max_u32_dpp v55, v55, v55 row_ror:4 row_mask:0xf bank_mask:0xf bound_ctrl:1
	v_max_u32_dpp v57, v57, v57 row_ror:2 row_mask:0xf bank_mask:0xf bound_ctrl:1
	v_max_u32_dpp v54, v54, v54 row_ror:4 row_mask:0xf bank_mask:0xf bound_ctrl:1
	v_max_u32_dpp v56, v56, v56 row_ror:4 row_mask:0xf bank_mask:0xf bound_ctrl:1
	v_max_u32_dpp v55, v55, v55 row_ror:8 row_mask:0xf bank_mask:0xf bound_ctrl:1
	v_max_u32_dpp v57, v57, v57 row_ror:4 row_mask:0xf bank_mask:0xf bound_ctrl:1
	v_max_u32_dpp v54, v54, v54 row_ror:8 row_mask:0xf bank_mask:0xf bound_ctrl:1
	v_max_u32_dpp v56, v56, v56 row_ror:8 row_mask:0xf bank_mask:0xf bound_ctrl:1
	v_max_u32_dpp v57, v57, v57 row_ror:8 row_mask:0xf bank_mask:0xf bound_ctrl:1
	v_cmp_eq_u32_e64 s[84:85], v72, v55
	v_cmp_eq_u32_e64 s[86:87], v80, v54
	v_cmp_eq_u32_e64 s[88:89], v88, v56
	v_cmp_eq_u32_e64 s[90:91], v96, v57
	s_mov_b64 exec, s[84:85]
	v_pk_mov_b32 v[72:73], v[72:73], v[74:75] op_sel:[1,0] op_sel_hi:[1,0]
	v_pk_mov_b32 v[74:75], v[74:75], v[76:77] op_sel:[1,0] op_sel_hi:[1,0]
	v_pk_mov_b32 v[76:77], v[76:77], v[78:79] op_sel:[1,0] op_sel_hi:[1,0]
	s_mov_b64 exec, s[86:87]
	v_pk_mov_b32 v[80:81], v[80:81], v[82:83] op_sel:[1,0] op_sel_hi:[1,0]
	v_pk_mov_b32 v[82:83], v[82:83], v[84:85] op_sel:[1,0] op_sel_hi:[1,0]
	v_pk_mov_b32 v[84:85], v[84:85], v[86:87] op_sel:[1,0] op_sel_hi:[1,0]
	s_mov_b64 exec, s[88:89]
	v_pk_mov_b32 v[88:89], v[88:89], v[90:91] op_sel:[1,0] op_sel_hi:[1,0]
	v_pk_mov_b32 v[90:91], v[90:91], v[92:93] op_sel:[1,0] op_sel_hi:[1,0]
	v_pk_mov_b32 v[92:93], v[92:93], v[94:95] op_sel:[1,0] op_sel_hi:[1,0]
	s_mov_b64 exec, s[90:91]
	v_pk_mov_b32 v[96:97], v[96:97], v[98:99] op_sel:[1,0] op_sel_hi:[1,0]
	v_pk_mov_b32 v[98:99], v[98:99], v[100:101] op_sel:[1,0] op_sel_hi:[1,0]
	v_pk_mov_b32 v[100:101], v[100:101], v[102:103] op_sel:[1,0] op_sel_hi:[1,0]
	s_lshl_b64 exec, s[78:79], s40
	s_add_i32 s40, s40, 1
	v_pk_mov_b32 v[18:19], v[54:55], v[54:55] op_sel:[0,1] op_sel_hi:[0,1]
	v_pk_mov_b32 v[20:21], v[56:57], v[56:57] op_sel:[0,1] op_sel_hi:[0,1]
	s_mov_b64 exec, -1
	v_max_u32_dpp v55, v72, v72 row_ror:1 row_mask:0xf bank_mask:0xf bound_ctrl:1
	v_max_u32_dpp v54, v80, v80 row_ror:1 row_mask:0xf bank_mask:0xf bound_ctrl:1
	v_max_u32_dpp v56, v88, v88 row_ror:1 row_mask:0xf bank_mask:0xf bound_ctrl:1
	v_max_u32_dpp v55, v55, v55 row_ror:2 row_mask:0xf bank_mask:0xf bound_ctrl:1
	v_max_u32_dpp v57, v96, v96 row_ror:1 row_mask:0xf bank_mask:0xf bound_ctrl:1
	v_max_u32_dpp v54, v54, v54 row_ror:2 row_mask:0xf bank_mask:0xf bound_ctrl:1
	v_max_u32_dpp v56, v56, v56 row_ror:2 row_mask:0xf bank_mask:0xf bound_ctrl:1
	v_max_u32_dpp v55, v55, v55 row_ror:4 row_mask:0xf bank_mask:0xf bound_ctrl:1
	v_max_u32_dpp v57, v57, v57 row_ror:2 row_mask:0xf bank_mask:0xf bound_ctrl:1
	v_max_u32_dpp v54, v54, v54 row_ror:4 row_mask:0xf bank_mask:0xf bound_ctrl:1
	v_max_u32_dpp v56, v56, v56 row_ror:4 row_mask:0xf bank_mask:0xf bound_ctrl:1
	v_max_u32_dpp v55, v55, v55 row_ror:8 row_mask:0xf bank_mask:0xf bound_ctrl:1
	v_max_u32_dpp v57, v57, v57 row_ror:4 row_mask:0xf bank_mask:0xf bound_ctrl:1
	v_max_u32_dpp v54, v54, v54 row_ror:8 row_mask:0xf bank_mask:0xf bound_ctrl:1
	v_max_u32_dpp v56, v56, v56 row_ror:8 row_mask:0xf bank_mask:0xf bound_ctrl:1
	v_max_u32_dpp v57, v57, v57 row_ror:8 row_mask:0xf bank_mask:0xf bound_ctrl:1
	v_cmp_eq_u32_e64 s[84:85], v72, v55
	v_cmp_eq_u32_e64 s[86:87], v80, v54
	v_cmp_eq_u32_e64 s[88:89], v88, v56
	v_cmp_eq_u32_e64 s[90:91], v96, v57
	s_mov_b64 exec, s[84:85]
	v_pk_mov_b32 v[72:73], v[72:73], v[74:75] op_sel:[1,0] op_sel_hi:[1,0]
	v_pk_mov_b32 v[74:75], v[74:75], v[76:77] op_sel:[1,0] op_sel_hi:[1,0]
	v_pk_mov_b32 v[76:77], v[76:77], v[78:79] op_sel:[1,0] op_sel_hi:[1,0]
	s_mov_b64 exec, s[86:87]
	v_pk_mov_b32 v[80:81], v[80:81], v[82:83] op_sel:[1,0] op_sel_hi:[1,0]
	v_pk_mov_b32 v[82:83], v[82:83], v[84:85] op_sel:[1,0] op_sel_hi:[1,0]
	v_pk_mov_b32 v[84:85], v[84:85], v[86:87] op_sel:[1,0] op_sel_hi:[1,0]
	s_mov_b64 exec, s[88:89]
	v_pk_mov_b32 v[88:89], v[88:89], v[90:91] op_sel:[1,0] op_sel_hi:[1,0]
	v_pk_mov_b32 v[90:91], v[90:91], v[92:93] op_sel:[1,0] op_sel_hi:[1,0]
	v_pk_mov_b32 v[92:93], v[92:93], v[94:95] op_sel:[1,0] op_sel_hi:[1,0]
	s_mov_b64 exec, s[90:91]
	v_pk_mov_b32 v[96:97], v[96:97], v[98:99] op_sel:[1,0] op_sel_hi:[1,0]
	v_pk_mov_b32 v[98:99], v[98:99], v[100:101] op_sel:[1,0] op_sel_hi:[1,0]
	v_pk_mov_b32 v[100:101], v[100:101], v[102:103] op_sel:[1,0] op_sel_hi:[1,0]
	s_lshl_b64 exec, s[78:79], s40
	s_add_i32 s40, s40, 1
	v_pk_mov_b32 v[18:19], v[54:55], v[54:55] op_sel:[0,1] op_sel_hi:[0,1]
	v_pk_mov_b32 v[20:21], v[56:57], v[56:57] op_sel:[0,1] op_sel_hi:[0,1]
	s_mov_b64 exec, -1
	v_max_u32_dpp v55, v72, v72 row_ror:1 row_mask:0xf bank_mask:0xf bound_ctrl:1
	v_max_u32_dpp v54, v80, v80 row_ror:1 row_mask:0xf bank_mask:0xf bound_ctrl:1
	v_max_u32_dpp v56, v88, v88 row_ror:1 row_mask:0xf bank_mask:0xf bound_ctrl:1
	v_max_u32_dpp v55, v55, v55 row_ror:2 row_mask:0xf bank_mask:0xf bound_ctrl:1
	v_max_u32_dpp v57, v96, v96 row_ror:1 row_mask:0xf bank_mask:0xf bound_ctrl:1
	v_max_u32_dpp v54, v54, v54 row_ror:2 row_mask:0xf bank_mask:0xf bound_ctrl:1
	v_max_u32_dpp v56, v56, v56 row_ror:2 row_mask:0xf bank_mask:0xf bound_ctrl:1
	v_max_u32_dpp v55, v55, v55 row_ror:4 row_mask:0xf bank_mask:0xf bound_ctrl:1
	v_max_u32_dpp v57, v57, v57 row_ror:2 row_mask:0xf bank_mask:0xf bound_ctrl:1
	v_max_u32_dpp v54, v54, v54 row_ror:4 row_mask:0xf bank_mask:0xf bound_ctrl:1
	v_max_u32_dpp v56, v56, v56 row_ror:4 row_mask:0xf bank_mask:0xf bound_ctrl:1
	v_max_u32_dpp v55, v55, v55 row_ror:8 row_mask:0xf bank_mask:0xf bound_ctrl:1
	v_max_u32_dpp v57, v57, v57 row_ror:4 row_mask:0xf bank_mask:0xf bound_ctrl:1
	v_max_u32_dpp v54, v54, v54 row_ror:8 row_mask:0xf bank_mask:0xf bound_ctrl:1
	v_max_u32_dpp v56, v56, v56 row_ror:8 row_mask:0xf bank_mask:0xf bound_ctrl:1
	v_max_u32_dpp v57, v57, v57 row_ror:8 row_mask:0xf bank_mask:0xf bound_ctrl:1
	v_cmp_eq_u32_e64 s[84:85], v72, v55
	v_cmp_eq_u32_e64 s[86:87], v80, v54
	v_cmp_eq_u32_e64 s[88:89], v88, v56
	v_cmp_eq_u32_e64 s[90:91], v96, v57
	s_mov_b64 exec, s[84:85]
	v_pk_mov_b32 v[72:73], v[72:73], v[74:75] op_sel:[1,0] op_sel_hi:[1,0]
	v_pk_mov_b32 v[74:75], v[74:75], v[76:77] op_sel:[1,0] op_sel_hi:[1,0]
	s_mov_b64 exec, s[86:87]
	v_pk_mov_b32 v[80:81], v[80:81], v[82:83] op_sel:[1,0] op_sel_hi:[1,0]
	v_pk_mov_b32 v[82:83], v[82:83], v[84:85] op_sel:[1,0] op_sel_hi:[1,0]
	s_mov_b64 exec, s[88:89]
	v_pk_mov_b32 v[88:89], v[88:89], v[90:91] op_sel:[1,0] op_sel_hi:[1,0]
	v_pk_mov_b32 v[90:91], v[90:91], v[92:93] op_sel:[1,0] op_sel_hi:[1,0]
	s_mov_b64 exec, s[90:91]
	v_pk_mov_b32 v[96:97], v[96:97], v[98:99] op_sel:[1,0] op_sel_hi:[1,0]
	v_pk_mov_b32 v[98:99], v[98:99], v[100:101] op_sel:[1,0] op_sel_hi:[1,0]
	s_lshl_b64 exec, s[78:79], s40
	s_add_i32 s40, s40, 1
	v_pk_mov_b32 v[18:19], v[54:55], v[54:55] op_sel:[0,1] op_sel_hi:[0,1]
	v_pk_mov_b32 v[20:21], v[56:57], v[56:57] op_sel:[0,1] op_sel_hi:[0,1]
	s_mov_b64 exec, -1
	v_max_u32_dpp v55, v72, v72 row_ror:1 row_mask:0xf bank_mask:0xf bound_ctrl:1
	v_max_u32_dpp v54, v80, v80 row_ror:1 row_mask:0xf bank_mask:0xf bound_ctrl:1
	v_max_u32_dpp v56, v88, v88 row_ror:1 row_mask:0xf bank_mask:0xf bound_ctrl:1
	v_max_u32_dpp v55, v55, v55 row_ror:2 row_mask:0xf bank_mask:0xf bound_ctrl:1
	v_max_u32_dpp v57, v96, v96 row_ror:1 row_mask:0xf bank_mask:0xf bound_ctrl:1
	v_max_u32_dpp v54, v54, v54 row_ror:2 row_mask:0xf bank_mask:0xf bound_ctrl:1
	v_max_u32_dpp v56, v56, v56 row_ror:2 row_mask:0xf bank_mask:0xf bound_ctrl:1
	v_max_u32_dpp v55, v55, v55 row_ror:4 row_mask:0xf bank_mask:0xf bound_ctrl:1
	v_max_u32_dpp v57, v57, v57 row_ror:2 row_mask:0xf bank_mask:0xf bound_ctrl:1
	v_max_u32_dpp v54, v54, v54 row_ror:4 row_mask:0xf bank_mask:0xf bound_ctrl:1
	v_max_u32_dpp v56, v56, v56 row_ror:4 row_mask:0xf bank_mask:0xf bound_ctrl:1
	v_max_u32_dpp v55, v55, v55 row_ror:8 row_mask:0xf bank_mask:0xf bound_ctrl:1
	v_max_u32_dpp v57, v57, v57 row_ror:4 row_mask:0xf bank_mask:0xf bound_ctrl:1
	v_max_u32_dpp v54, v54, v54 row_ror:8 row_mask:0xf bank_mask:0xf bound_ctrl:1
	v_max_u32_dpp v56, v56, v56 row_ror:8 row_mask:0xf bank_mask:0xf bound_ctrl:1
	v_max_u32_dpp v57, v57, v57 row_ror:8 row_mask:0xf bank_mask:0xf bound_ctrl:1
	v_cmp_eq_u32_e64 s[84:85], v72, v55
	v_cmp_eq_u32_e64 s[86:87], v80, v54
	v_cmp_eq_u32_e64 s[88:89], v88, v56
	v_cmp_eq_u32_e64 s[90:91], v96, v57
	s_mov_b64 exec, s[84:85]
	v_pk_mov_b32 v[72:73], v[72:73], v[74:75] op_sel:[1,0] op_sel_hi:[1,0]
	v_pk_mov_b32 v[74:75], v[74:75], v[76:77] op_sel:[1,0] op_sel_hi:[1,0]
	s_mov_b64 exec, s[86:87]
	v_pk_mov_b32 v[80:81], v[80:81], v[82:83] op_sel:[1,0] op_sel_hi:[1,0]
	v_pk_mov_b32 v[82:83], v[82:83], v[84:85] op_sel:[1,0] op_sel_hi:[1,0]
	s_mov_b64 exec, s[88:89]
	v_pk_mov_b32 v[88:89], v[88:89], v[90:91] op_sel:[1,0] op_sel_hi:[1,0]
	v_pk_mov_b32 v[90:91], v[90:91], v[92:93] op_sel:[1,0] op_sel_hi:[1,0]
	s_mov_b64 exec, s[90:91]
	v_pk_mov_b32 v[96:97], v[96:97], v[98:99] op_sel:[1,0] op_sel_hi:[1,0]
	v_pk_mov_b32 v[98:99], v[98:99], v[100:101] op_sel:[1,0] op_sel_hi:[1,0]
	s_lshl_b64 exec, s[78:79], s40
	s_add_i32 s40, s40, 1
	v_pk_mov_b32 v[18:19], v[54:55], v[54:55] op_sel:[0,1] op_sel_hi:[0,1]
	v_pk_mov_b32 v[20:21], v[56:57], v[56:57] op_sel:[0,1] op_sel_hi:[0,1]
	s_mov_b64 exec, -1
	v_max_u32_dpp v55, v72, v72 row_ror:1 row_mask:0xf bank_mask:0xf bound_ctrl:1
	v_max_u32_dpp v54, v80, v80 row_ror:1 row_mask:0xf bank_mask:0xf bound_ctrl:1
	v_max_u32_dpp v56, v88, v88 row_ror:1 row_mask:0xf bank_mask:0xf bound_ctrl:1
	v_max_u32_dpp v55, v55, v55 row_ror:2 row_mask:0xf bank_mask:0xf bound_ctrl:1
	v_max_u32_dpp v57, v96, v96 row_ror:1 row_mask:0xf bank_mask:0xf bound_ctrl:1
	v_max_u32_dpp v54, v54, v54 row_ror:2 row_mask:0xf bank_mask:0xf bound_ctrl:1
	v_max_u32_dpp v56, v56, v56 row_ror:2 row_mask:0xf bank_mask:0xf bound_ctrl:1
	v_max_u32_dpp v55, v55, v55 row_ror:4 row_mask:0xf bank_mask:0xf bound_ctrl:1
	v_max_u32_dpp v57, v57, v57 row_ror:2 row_mask:0xf bank_mask:0xf bound_ctrl:1
	v_max_u32_dpp v54, v54, v54 row_ror:4 row_mask:0xf bank_mask:0xf bound_ctrl:1
	v_max_u32_dpp v56, v56, v56 row_ror:4 row_mask:0xf bank_mask:0xf bound_ctrl:1
	v_max_u32_dpp v55, v55, v55 row_ror:8 row_mask:0xf bank_mask:0xf bound_ctrl:1
	v_max_u32_dpp v57, v57, v57 row_ror:4 row_mask:0xf bank_mask:0xf bound_ctrl:1
	v_max_u32_dpp v54, v54, v54 row_ror:8 row_mask:0xf bank_mask:0xf bound_ctrl:1
	v_max_u32_dpp v56, v56, v56 row_ror:8 row_mask:0xf bank_mask:0xf bound_ctrl:1
	v_max_u32_dpp v57, v57, v57 row_ror:8 row_mask:0xf bank_mask:0xf bound_ctrl:1
	v_cmp_eq_u32_e64 s[84:85], v72, v55
	v_cmp_eq_u32_e64 s[86:87], v80, v54
	v_cmp_eq_u32_e64 s[88:89], v88, v56
	v_cmp_eq_u32_e64 s[90:91], v96, v57
	s_mov_b64 exec, s[84:85]
	v_pk_mov_b32 v[72:73], v[72:73], v[74:75] op_sel:[1,0] op_sel_hi:[1,0]
	s_mov_b64 exec, s[86:87]
	v_pk_mov_b32 v[80:81], v[80:81], v[82:83] op_sel:[1,0] op_sel_hi:[1,0]
	s_mov_b64 exec, s[88:89]
	v_pk_mov_b32 v[88:89], v[88:89], v[90:91] op_sel:[1,0] op_sel_hi:[1,0]
	s_mov_b64 exec, s[90:91]
	v_pk_mov_b32 v[96:97], v[96:97], v[98:99] op_sel:[1,0] op_sel_hi:[1,0]
	s_lshl_b64 exec, s[78:79], s40
	s_add_i32 s40, s40, 1
	v_pk_mov_b32 v[18:19], v[54:55], v[54:55] op_sel:[0,1] op_sel_hi:[0,1]
	v_pk_mov_b32 v[20:21], v[56:57], v[56:57] op_sel:[0,1] op_sel_hi:[0,1]
	s_mov_b64 exec, -1
	v_max_u32_dpp v55, v72, v72 row_ror:1 row_mask:0xf bank_mask:0xf bound_ctrl:1
	v_max_u32_dpp v54, v80, v80 row_ror:1 row_mask:0xf bank_mask:0xf bound_ctrl:1
	v_max_u32_dpp v56, v88, v88 row_ror:1 row_mask:0xf bank_mask:0xf bound_ctrl:1
	v_max_u32_dpp v55, v55, v55 row_ror:2 row_mask:0xf bank_mask:0xf bound_ctrl:1
	v_max_u32_dpp v57, v96, v96 row_ror:1 row_mask:0xf bank_mask:0xf bound_ctrl:1
	v_max_u32_dpp v54, v54, v54 row_ror:2 row_mask:0xf bank_mask:0xf bound_ctrl:1
	v_max_u32_dpp v56, v56, v56 row_ror:2 row_mask:0xf bank_mask:0xf bound_ctrl:1
	v_max_u32_dpp v55, v55, v55 row_ror:4 row_mask:0xf bank_mask:0xf bound_ctrl:1
	v_max_u32_dpp v57, v57, v57 row_ror:2 row_mask:0xf bank_mask:0xf bound_ctrl:1
	v_max_u32_dpp v54, v54, v54 row_ror:4 row_mask:0xf bank_mask:0xf bound_ctrl:1
	v_max_u32_dpp v56, v56, v56 row_ror:4 row_mask:0xf bank_mask:0xf bound_ctrl:1
	v_max_u32_dpp v55, v55, v55 row_ror:8 row_mask:0xf bank_mask:0xf bound_ctrl:1
	v_max_u32_dpp v57, v57, v57 row_ror:4 row_mask:0xf bank_mask:0xf bound_ctrl:1
	v_max_u32_dpp v54, v54, v54 row_ror:8 row_mask:0xf bank_mask:0xf bound_ctrl:1
	v_max_u32_dpp v56, v56, v56 row_ror:8 row_mask:0xf bank_mask:0xf bound_ctrl:1
	v_max_u32_dpp v57, v57, v57 row_ror:8 row_mask:0xf bank_mask:0xf bound_ctrl:1
	v_cmp_eq_u32_e64 s[84:85], v72, v55
	v_cmp_eq_u32_e64 s[86:87], v80, v54
	v_cmp_eq_u32_e64 s[88:89], v88, v56
	v_cmp_eq_u32_e64 s[90:91], v96, v57
	s_mov_b64 exec, s[84:85]
	v_pk_mov_b32 v[72:73], v[72:73], v[74:75] op_sel:[1,0] op_sel_hi:[1,0]
	s_mov_b64 exec, s[86:87]
	v_pk_mov_b32 v[80:81], v[80:81], v[82:83] op_sel:[1,0] op_sel_hi:[1,0]
	s_mov_b64 exec, s[88:89]
	v_pk_mov_b32 v[88:89], v[88:89], v[90:91] op_sel:[1,0] op_sel_hi:[1,0]
	s_mov_b64 exec, s[90:91]
	v_pk_mov_b32 v[96:97], v[96:97], v[98:99] op_sel:[1,0] op_sel_hi:[1,0]
	s_lshl_b64 exec, s[78:79], s40
	s_add_i32 s40, s40, 1
	v_pk_mov_b32 v[18:19], v[54:55], v[54:55] op_sel:[0,1] op_sel_hi:[0,1]
	v_pk_mov_b32 v[20:21], v[56:57], v[56:57] op_sel:[0,1] op_sel_hi:[0,1]
	s_mov_b64 exec, -1
	v_max_u32_dpp v55, v72, v72 row_ror:1 row_mask:0xf bank_mask:0xf bound_ctrl:1
	v_max_u32_dpp v54, v80, v80 row_ror:1 row_mask:0xf bank_mask:0xf bound_ctrl:1
	v_max_u32_dpp v56, v88, v88 row_ror:1 row_mask:0xf bank_mask:0xf bound_ctrl:1
	v_max_u32_dpp v55, v55, v55 row_ror:2 row_mask:0xf bank_mask:0xf bound_ctrl:1
	v_max_u32_dpp v57, v96, v96 row_ror:1 row_mask:0xf bank_mask:0xf bound_ctrl:1
	v_max_u32_dpp v54, v54, v54 row_ror:2 row_mask:0xf bank_mask:0xf bound_ctrl:1
	v_max_u32_dpp v56, v56, v56 row_ror:2 row_mask:0xf bank_mask:0xf bound_ctrl:1
	v_max_u32_dpp v55, v55, v55 row_ror:4 row_mask:0xf bank_mask:0xf bound_ctrl:1
	v_max_u32_dpp v57, v57, v57 row_ror:2 row_mask:0xf bank_mask:0xf bound_ctrl:1
	v_max_u32_dpp v54, v54, v54 row_ror:4 row_mask:0xf bank_mask:0xf bound_ctrl:1
	v_max_u32_dpp v56, v56, v56 row_ror:4 row_mask:0xf bank_mask:0xf bound_ctrl:1
	v_max_u32_dpp v55, v55, v55 row_ror:8 row_mask:0xf bank_mask:0xf bound_ctrl:1
	v_max_u32_dpp v57, v57, v57 row_ror:4 row_mask:0xf bank_mask:0xf bound_ctrl:1
	v_max_u32_dpp v54, v54, v54 row_ror:8 row_mask:0xf bank_mask:0xf bound_ctrl:1
	v_max_u32_dpp v56, v56, v56 row_ror:8 row_mask:0xf bank_mask:0xf bound_ctrl:1
	v_max_u32_dpp v57, v57, v57 row_ror:8 row_mask:0xf bank_mask:0xf bound_ctrl:1
	s_lshl_b64 exec, s[78:79], s40
	v_pk_mov_b32 v[18:19], v[54:55], v[54:55] op_sel:[0,1] op_sel_hi:[0,1]
	v_pk_mov_b32 v[20:21], v[56:57], v[56:57] op_sel:[0,1] op_sel_hi:[0,1]
	s_mov_b64 exec, -1
	ds_read_b128 v[70:73], v184 offset:34816
	ds_read_b128 v[74:77], v184 offset:34880
	ds_read_b128 v[78:81], v184 offset:34944
	ds_read_b128 v[82:85], v184 offset:35008
	ds_read_b128 v[86:89], v184 offset:39168
	ds_read_b128 v[90:93], v184 offset:39232
	ds_read_b128 v[94:97], v184 offset:39296
	ds_read_b128 v[98:101], v184 offset:39360
	ds_read_b128 v[102:105], v184 offset:43520
	ds_read_b128 v[106:109], v184 offset:43584
	ds_read_b128 v[110:113], v184 offset:43648
	ds_read_b128 v[114:117], v184 offset:43712
	s_waitcnt vmcnt(0)
	s_waitcnt lgkmcnt(8)
	v_mfma_f32_16x16x32_bf16 v[22:25], v[12:15], v[70:73], 0
	v_mfma_f32_16x16x32_bf16 v[22:25], v[8:11], v[74:77], v[22:25]
	v_mfma_f32_16x16x32_bf16 v[22:25], v[4:7], v[78:81], v[22:25]
	v_mfma_f32_16x16x32_bf16 v[22:25], v[0:3], v[82:85], v[22:25]
	ds_read_b128 v[118:121], v184 offset:47872
	ds_read_b128 v[122:125], v184 offset:47936
	ds_read_b128 v[126:129], v184 offset:48000
	ds_read_b128 v[130:133], v184 offset:48064
	s_waitcnt lgkmcnt(8)
	v_mfma_f32_16x16x32_bf16 v[26:29], v[12:15], v[86:89], 0
	v_mfma_f32_16x16x32_bf16 v[26:29], v[8:11], v[90:93], v[26:29]
	v_mfma_f32_16x16x32_bf16 v[26:29], v[4:7], v[94:97], v[26:29]
	v_mfma_f32_16x16x32_bf16 v[26:29], v[0:3], v[98:101], v[26:29]
	ds_read_b128 v[70:73], v184 offset:52224
	ds_read_b128 v[74:77], v184 offset:52288
	ds_read_b128 v[78:81], v184 offset:52352
	ds_read_b128 v[82:85], v184 offset:52416
	s_waitcnt lgkmcnt(8)
	v_mfma_f32_16x16x32_bf16 v[30:33], v[12:15], v[102:105], 0
	v_mfma_f32_16x16x32_bf16 v[30:33], v[8:11], v[106:109], v[30:33]
	v_mfma_f32_16x16x32_bf16 v[30:33], v[4:7], v[110:113], v[30:33]
	v_mfma_f32_16x16x32_bf16 v[30:33], v[0:3], v[114:117], v[30:33]
	ds_read_b128 v[86:89], v184 offset:56576
	ds_read_b128 v[90:93], v184 offset:56640
	ds_read_b128 v[94:97], v184 offset:56704
	ds_read_b128 v[98:101], v184 offset:56768
	s_waitcnt lgkmcnt(8)
	v_mfma_f32_16x16x32_bf16 v[34:37], v[12:15], v[118:121], 0
	v_mfma_f32_16x16x32_bf16 v[34:37], v[8:11], v[122:125], v[34:37]
	v_mfma_f32_16x16x32_bf16 v[34:37], v[4:7], v[126:129], v[34:37]
	v_mfma_f32_16x16x32_bf16 v[34:37], v[0:3], v[130:133], v[34:37]
	ds_read_b128 v[102:105], v184 offset:60928
	ds_read_b128 v[106:109], v184 offset:60992
	ds_read_b128 v[110:113], v184 offset:61056
	ds_read_b128 v[114:117], v184 offset:61120
	s_waitcnt lgkmcnt(8)
	v_mfma_f32_16x16x32_bf16 v[38:41], v[12:15], v[70:73], 0
	v_mfma_f32_16x16x32_bf16 v[38:41], v[8:11], v[74:77], v[38:41]
	v_mfma_f32_16x16x32_bf16 v[38:41], v[4:7], v[78:81], v[38:41]
	v_mfma_f32_16x16x32_bf16 v[38:41], v[0:3], v[82:85], v[38:41]
	ds_read_b128 v[118:121], v184 offset:65280
	ds_read_b128 v[122:125], v184 offset:65344
	ds_read_b128 v[126:129], v184 offset:65408
	ds_read_b128 v[130:133], v184 offset:65472
	s_waitcnt lgkmcnt(8)
	v_mfma_f32_16x16x32_bf16 v[42:45], v[12:15], v[86:89], 0
	v_mfma_f32_16x16x32_bf16 v[42:45], v[8:11], v[90:93], v[42:45]
	v_mfma_f32_16x16x32_bf16 v[42:45], v[4:7], v[94:97], v[42:45]
	v_mfma_f32_16x16x32_bf16 v[42:45], v[0:3], v[98:101], v[42:45]
	s_waitcnt lgkmcnt(4)
	v_mfma_f32_16x16x32_bf16 v[46:49], v[12:15], v[102:105], 0
	v_mfma_f32_16x16x32_bf16 v[46:49], v[8:11], v[106:109], v[46:49]
	v_mfma_f32_16x16x32_bf16 v[46:49], v[4:7], v[110:113], v[46:49]
	v_mfma_f32_16x16x32_bf16 v[46:49], v[0:3], v[114:117], v[46:49]
	s_waitcnt lgkmcnt(0)
	v_mfma_f32_16x16x32_bf16 v[12:15], v[12:15], v[118:121], 0
	v_mfma_f32_16x16x32_bf16 v[8:11], v[8:11], v[122:125], v[12:15]
	v_mfma_f32_16x16x32_bf16 v[4:7], v[4:7], v[126:129], v[8:11]
	v_mfma_f32_16x16x32_bf16 v[0:3], v[0:3], v[130:133], v[4:7]
	s_nop 7
	s_nop 7
	s_mov_b32 s40, 0
	v_ashrrev_i32_e32 v4, 31, v3
	v_bitop3_b32 v3, v3, v4, v217 bitop3:0x1e
	v_and_or_b32 v3, v3, s67, v178
	v_ashrrev_i32_e32 v4, 31, v49
	v_bitop3_b32 v4, v49, v4, v217 bitop3:0x1e
	v_and_or_b32 v49, v4, s67, v177
	v_ashrrev_i32_e32 v4, 31, v45
	v_bitop3_b32 v4, v45, v4, v217 bitop3:0x1e
	v_and_or_b32 v45, v4, s67, v176
	v_ashrrev_i32_e32 v4, 31, v41
	v_bitop3_b32 v4, v41, v4, v217 bitop3:0x1e
	v_and_or_b32 v41, v4, s67, v175
	v_ashrrev_i32_e32 v4, 31, v37
	v_bitop3_b32 v4, v37, v4, v217 bitop3:0x1e
	v_and_or_b32 v37, v4, s67, v170
	v_ashrrev_i32_e32 v4, 31, v33
	v_bitop3_b32 v4, v33, v4, v217 bitop3:0x1e
	v_and_or_b32 v50, v4, s67, v181
	v_ashrrev_i32_e32 v4, 31, v29
	v_bitop3_b32 v4, v29, v4, v217 bitop3:0x1e
	v_and_or_b32 v51, v4, s67, v180
	v_ashrrev_i32_e32 v4, 31, v25
	v_bitop3_b32 v4, v25, v4, v217 bitop3:0x1e
	v_and_or_b32 v52, v4, s67, v179
	v_ashrrev_i32_e32 v4, 31, v2
	v_bitop3_b32 v2, v2, v4, v217 bitop3:0x1e
	v_and_or_b32 v2, v2, s67, v178
	v_ashrrev_i32_e32 v4, 31, v48
	v_bitop3_b32 v4, v48, v4, v217 bitop3:0x1e
	v_and_or_b32 v29, v4, s67, v177
	v_ashrrev_i32_e32 v4, 31, v44
	v_bitop3_b32 v4, v44, v4, v217 bitop3:0x1e
	v_and_or_b32 v33, v4, s67, v176
	v_ashrrev_i32_e32 v4, 31, v40
	v_bitop3_b32 v4, v40, v4, v217 bitop3:0x1e
	v_and_or_b32 v40, v4, s67, v175
	v_ashrrev_i32_e32 v4, 31, v36
	v_bitop3_b32 v4, v36, v4, v217 bitop3:0x1e
	v_and_or_b32 v36, v4, s67, v170
	v_ashrrev_i32_e32 v4, 31, v32
	v_bitop3_b32 v4, v32, v4, v217 bitop3:0x1e
	v_and_or_b32 v32, v4, s67, v181
	v_ashrrev_i32_e32 v4, 31, v28
	v_bitop3_b32 v4, v28, v4, v217 bitop3:0x1e
	v_and_or_b32 v28, v4, s67, v180
	v_ashrrev_i32_e32 v4, 31, v24
	v_bitop3_b32 v4, v24, v4, v217 bitop3:0x1e
	v_and_or_b32 v44, v4, s67, v179
	v_ashrrev_i32_e32 v4, 31, v1
	v_bitop3_b32 v1, v1, v4, v217 bitop3:0x1e
	v_and_or_b32 v1, v1, s67, v178
	v_ashrrev_i32_e32 v4, 31, v47
	v_bitop3_b32 v4, v47, v4, v217 bitop3:0x1e
	v_and_or_b32 v12, v4, s67, v177
	v_ashrrev_i32_e32 v4, 31, v43
	v_bitop3_b32 v4, v43, v4, v217 bitop3:0x1e
	v_and_or_b32 v13, v4, s67, v176
	v_ashrrev_i32_e32 v4, 31, v39
	v_bitop3_b32 v4, v39, v4, v217 bitop3:0x1e
	v_and_or_b32 v14, v4, s67, v175
	v_ashrrev_i32_e32 v4, 31, v35
	v_bitop3_b32 v4, v35, v4, v217 bitop3:0x1e
	v_and_or_b32 v15, v4, s67, v170
	v_max_u32_e32 v35, v41, v45
	v_ashrrev_i32_e32 v4, 31, v31
	v_bitop3_b32 v4, v31, v4, v217 bitop3:0x1e
	v_and_or_b32 v24, v4, s67, v181
	v_max_u32_e32 v31, v29, v2
	v_ashrrev_i32_e32 v4, 31, v27
	v_bitop3_b32 v4, v27, v4, v217 bitop3:0x1e
	v_and_or_b32 v25, v4, s67, v180
	v_min_u32_e32 v2, v29, v2
	v_ashrrev_i32_e32 v4, 31, v23
	v_bitop3_b32 v4, v23, v4, v217 bitop3:0x1e
	v_and_or_b32 v23, v4, s67, v179
	v_ashrrev_i32_e32 v4, 31, v0
	v_bitop3_b32 v0, v0, v4, v217 bitop3:0x1e
	v_and_or_b32 v0, v0, s67, v178
	v_ashrrev_i32_e32 v4, 31, v46
	v_bitop3_b32 v4, v46, v4, v217 bitop3:0x1e
	v_and_or_b32 v4, v4, s67, v177
	v_ashrrev_i32_e32 v5, 31, v42
	v_bitop3_b32 v5, v42, v5, v217 bitop3:0x1e
	v_and_or_b32 v5, v5, s67, v176
	v_ashrrev_i32_e32 v6, 31, v38
	v_bitop3_b32 v6, v38, v6, v217 bitop3:0x1e
	v_and_or_b32 v6, v6, s67, v175
	v_ashrrev_i32_e32 v7, 31, v34
	v_bitop3_b32 v7, v34, v7, v217 bitop3:0x1e
	v_and_or_b32 v7, v7, s67, v170
	v_ashrrev_i32_e32 v8, 31, v30
	v_bitop3_b32 v8, v30, v8, v217 bitop3:0x1e
	v_and_or_b32 v8, v8, s67, v181
	v_ashrrev_i32_e32 v9, 31, v26
	v_bitop3_b32 v9, v26, v9, v217 bitop3:0x1e
	v_and_or_b32 v9, v9, s67, v180
	v_ashrrev_i32_e32 v10, 31, v22
	v_bitop3_b32 v10, v22, v10, v217 bitop3:0x1e
	v_and_or_b32 v10, v10, s67, v179
	v_max_u32_e32 v11, v10, v9
	v_min_u32_e32 v9, v10, v9
	v_max_u32_e32 v10, v8, v7
	v_min_u32_e32 v7, v8, v7
	v_max_u32_e32 v8, v6, v5
	v_min_u32_e32 v5, v6, v5
	v_max_u32_e32 v6, v4, v0
	v_min_u32_e32 v0, v4, v0
	v_max_u32_e32 v22, v11, v10
	v_min_u32_e32 v4, v11, v10
	v_max_u32_e32 v10, v9, v7
	v_min_u32_e32 v7, v9, v7
	v_max_u32_e32 v9, v8, v6
	v_min_u32_e32 v6, v8, v6
	v_max_u32_e32 v8, v5, v0
	v_min_u32_e32 v0, v5, v0
	v_max_u32_e32 v5, v10, v4
	v_min_u32_e32 v10, v10, v4
	v_max_u32_e32 v11, v8, v6
	v_min_u32_e32 v6, v8, v6
	v_max_u32_e32 v80, v22, v9
	v_min_u32_e32 v8, v22, v9
	v_max_u32_e32 v9, v5, v11
	v_min_u32_e32 v11, v5, v11
	v_max_u32_e32 v22, v10, v6
	v_min_u32_e32 v26, v10, v6
	v_max_u32_e32 v6, v7, v0
	v_min_u32_e32 v87, v7, v0
	v_max_u32_e32 v0, v22, v8
	v_min_u32_e32 v10, v22, v8
	v_max_u32_e32 v22, v6, v11
	v_min_u32_e32 v11, v6, v11
	v_max_u32_e32 v81, v9, v0
	v_min_u32_e32 v82, v9, v0
	v_max_u32_e32 v83, v22, v10
	v_min_u32_e32 v84, v22, v10
	v_max_u32_e32 v0, v23, v25
	v_min_u32_e32 v22, v23, v25
	v_max_u32_e32 v23, v24, v15
	v_min_u32_e32 v15, v24, v15
	v_max_u32_e32 v24, v14, v13
	v_min_u32_e32 v13, v14, v13
	v_max_u32_e32 v14, v12, v1
	v_min_u32_e32 v1, v12, v1
	v_max_u32_e32 v25, v0, v23
	v_min_u32_e32 v0, v0, v23
	v_max_u32_e32 v12, v22, v15
	v_min_u32_e32 v15, v22, v15
	v_max_u32_e32 v22, v24, v14
	v_min_u32_e32 v14, v24, v14
	v_max_u32_e32 v23, v13, v1
	v_min_u32_e32 v1, v13, v1
	v_max_u32_e32 v13, v12, v0
	v_min_u32_e32 v0, v12, v0
	v_max_u32_e32 v24, v23, v14
	v_min_u32_e32 v14, v23, v14
	v_max_u32_e32 v72, v25, v22
	v_min_u32_e32 v22, v25, v22
	v_max_u32_e32 v23, v13, v24
	v_min_u32_e32 v24, v13, v24
	v_max_u32_e32 v25, v0, v14
	v_min_u32_e32 v0, v0, v14
	v_max_u32_e32 v14, v15, v1
	v_max_u32_e32 v85, v11, v26
	v_min_u32_e32 v86, v11, v26
	v_min_u32_e32 v79, v15, v1
	v_max_u32_e32 v1, v25, v22
	v_min_u32_e32 v25, v25, v22
	v_max_u32_e32 v26, v14, v24
	v_min_u32_e32 v27, v14, v24
	v_max_u32_e32 v73, v23, v1
	v_min_u32_e32 v74, v23, v1
	v_max_u32_e32 v75, v26, v25
	v_min_u32_e32 v76, v26, v25
	v_max_u32_e32 v77, v27, v0
	v_min_u32_e32 v78, v27, v0
	v_max_u32_e32 v0, v44, v28
	v_min_u32_e32 v1, v44, v28
	v_max_u32_e32 v26, v32, v36
	v_min_u32_e32 v27, v32, v36
	v_max_u32_e32 v28, v40, v33
	v_min_u32_e32 v30, v40, v33
	v_max_u32_e32 v29, v0, v26
	v_min_u32_e32 v0, v0, v26
	v_max_u32_e32 v26, v1, v27
	v_min_u32_e32 v1, v1, v27
	v_max_u32_e32 v27, v28, v31
	v_min_u32_e32 v28, v28, v31
	v_max_u32_e32 v31, v30, v2
	v_min_u32_e32 v2, v30, v2
	v_max_u32_e32 v30, v26, v0
	v_min_u32_e32 v0, v26, v0
	v_max_u32_e32 v32, v31, v28
	v_min_u32_e32 v28, v31, v28
	v_max_u32_e32 v88, v29, v27
	v_min_u32_e32 v29, v29, v27
	v_max_u32_e32 v31, v30, v32
	v_min_u32_e32 v30, v30, v32
	v_max_u32_e32 v32, v0, v28
	v_min_u32_e32 v0, v0, v28
	v_max_u32_e32 v28, v1, v2
	v_min_u32_e32 v95, v1, v2
	v_max_u32_e32 v1, v32, v29
	v_min_u32_e32 v2, v32, v29
	v_max_u32_e32 v32, v28, v30
	v_min_u32_e32 v33, v28, v30
	v_max_u32_e32 v89, v31, v1
	v_min_u32_e32 v90, v31, v1
	v_max_u32_e32 v91, v32, v2
	v_min_u32_e32 v92, v32, v2
	v_max_u32_e32 v93, v33, v0
	v_min_u32_e32 v94, v33, v0
	v_max_u32_e32 v0, v52, v51
	v_min_u32_e32 v1, v52, v51
	v_max_u32_e32 v2, v50, v37
	v_min_u32_e32 v34, v50, v37
	v_min_u32_e32 v36, v41, v45
	v_max_u32_e32 v37, v49, v3
	v_min_u32_e32 v3, v49, v3
	v_max_u32_e32 v38, v0, v2
	v_min_u32_e32 v0, v0, v2
	v_max_u32_e32 v2, v1, v34
	v_min_u32_e32 v1, v1, v34
	v_max_u32_e32 v39, v35, v37
	v_min_u32_e32 v34, v35, v37
	v_max_u32_e32 v35, v36, v3
	v_min_u32_e32 v3, v36, v3
	v_max_u32_e32 v36, v2, v0
	v_min_u32_e32 v0, v2, v0
	v_max_u32_e32 v2, v35, v34
	v_min_u32_e32 v35, v35, v34
	v_max_u32_e32 v96, v38, v39
	v_min_u32_e32 v37, v38, v39
	v_max_u32_e32 v38, v36, v2
	v_min_u32_e32 v2, v36, v2
	v_max_u32_e32 v36, v0, v35
	v_max_u32_e32 v39, v1, v3
	v_min_u32_e32 v0, v0, v35
	v_min_u32_e32 v103, v1, v3
	v_max_u32_e32 v1, v36, v37
	v_min_u32_e32 v3, v36, v37
	v_max_u32_e32 v40, v39, v2
	v_min_u32_e32 v2, v39, v2
	v_max_u32_e32 v97, v38, v1
	v_min_u32_e32 v98, v38, v1
	v_max_u32_e32 v99, v40, v3
	v_min_u32_e32 v100, v40, v3
	v_max_u32_e32 v101, v2, v0
	v_min_u32_e32 v102, v2, v0
	v_mov_b32_e32 v0, 0
	v_mov_b32_e32 v1, 0
	v_mov_b32_e32 v2, 0
	v_mov_b32_e32 v3, 0
.LBB0_1349:
	v_max_u32_dpp v43, v72, v72 row_ror:1 row_mask:0xf bank_mask:0xf bound_ctrl:1
	v_max_u32_dpp v42, v80, v80 row_ror:1 row_mask:0xf bank_mask:0xf bound_ctrl:1
	v_max_u32_dpp v44, v88, v88 row_ror:1 row_mask:0xf bank_mask:0xf bound_ctrl:1
	v_max_u32_dpp v43, v43, v43 row_ror:2 row_mask:0xf bank_mask:0xf bound_ctrl:1
	v_max_u32_dpp v45, v96, v96 row_ror:1 row_mask:0xf bank_mask:0xf bound_ctrl:1
	v_max_u32_dpp v42, v42, v42 row_ror:2 row_mask:0xf bank_mask:0xf bound_ctrl:1
	v_max_u32_dpp v44, v44, v44 row_ror:2 row_mask:0xf bank_mask:0xf bound_ctrl:1
	v_max_u32_dpp v43, v43, v43 row_ror:4 row_mask:0xf bank_mask:0xf bound_ctrl:1
	v_max_u32_dpp v45, v45, v45 row_ror:2 row_mask:0xf bank_mask:0xf bound_ctrl:1
	v_max_u32_dpp v42, v42, v42 row_ror:4 row_mask:0xf bank_mask:0xf bound_ctrl:1
	v_max_u32_dpp v44, v44, v44 row_ror:4 row_mask:0xf bank_mask:0xf bound_ctrl:1
	v_max_u32_dpp v43, v43, v43 row_ror:8 row_mask:0xf bank_mask:0xf bound_ctrl:1
	v_max_u32_dpp v45, v45, v45 row_ror:4 row_mask:0xf bank_mask:0xf bound_ctrl:1
	v_max_u32_dpp v42, v42, v42 row_ror:8 row_mask:0xf bank_mask:0xf bound_ctrl:1
	v_max_u32_dpp v44, v44, v44 row_ror:8 row_mask:0xf bank_mask:0xf bound_ctrl:1
	v_max_u32_dpp v45, v45, v45 row_ror:8 row_mask:0xf bank_mask:0xf bound_ctrl:1
	v_cmp_eq_u32_e64 s[84:85], v72, v43
	v_cmp_eq_u32_e64 s[86:87], v80, v42
	v_cmp_eq_u32_e64 s[88:89], v88, v44
	v_cmp_eq_u32_e64 s[90:91], v96, v45
	s_mov_b64 exec, s[84:85]
	v_pk_mov_b32 v[72:73], v[72:73], v[74:75] op_sel:[1,0] op_sel_hi:[1,0]
	v_pk_mov_b32 v[74:75], v[74:75], v[76:77] op_sel:[1,0] op_sel_hi:[1,0]
	v_pk_mov_b32 v[76:77], v[76:77], v[78:79] op_sel:[1,0] op_sel_hi:[1,0]
	v_pk_mov_b32 v[78:79], v[78:79], v[134:135] op_sel:[1,0] op_sel_hi:[1,0]
	s_mov_b64 exec, s[86:87]
	v_pk_mov_b32 v[80:81], v[80:81], v[82:83] op_sel:[1,0] op_sel_hi:[1,0]
	v_pk_mov_b32 v[82:83], v[82:83], v[84:85] op_sel:[1,0] op_sel_hi:[1,0]
	v_pk_mov_b32 v[84:85], v[84:85], v[86:87] op_sel:[1,0] op_sel_hi:[1,0]
	v_pk_mov_b32 v[86:87], v[86:87], v[134:135] op_sel:[1,0] op_sel_hi:[1,0]
	s_mov_b64 exec, s[88:89]
	v_pk_mov_b32 v[88:89], v[88:89], v[90:91] op_sel:[1,0] op_sel_hi:[1,0]
	v_pk_mov_b32 v[90:91], v[90:91], v[92:93] op_sel:[1,0] op_sel_hi:[1,0]
	v_pk_mov_b32 v[92:93], v[92:93], v[94:95] op_sel:[1,0] op_sel_hi:[1,0]
	v_pk_mov_b32 v[94:95], v[94:95], v[134:135] op_sel:[1,0] op_sel_hi:[1,0]
	s_mov_b64 exec, s[90:91]
	v_pk_mov_b32 v[96:97], v[96:97], v[98:99] op_sel:[1,0] op_sel_hi:[1,0]
	v_pk_mov_b32 v[98:99], v[98:99], v[100:101] op_sel:[1,0] op_sel_hi:[1,0]
	v_pk_mov_b32 v[100:101], v[100:101], v[102:103] op_sel:[1,0] op_sel_hi:[1,0]
	v_pk_mov_b32 v[102:103], v[102:103], v[134:135] op_sel:[1,0] op_sel_hi:[1,0]
	s_lshl_b64 exec, s[78:79], s40
	s_add_i32 s40, s40, 1
	v_pk_mov_b32 v[0:1], v[42:43], v[42:43] op_sel:[0,1] op_sel_hi:[0,1]
	v_pk_mov_b32 v[2:3], v[44:45], v[44:45] op_sel:[0,1] op_sel_hi:[0,1]
	s_mov_b64 exec, -1
	s_cmp_lg_u32 s40, 8
	s_cbranch_scc1 .LBB0_1349
	v_max_u32_dpp v43, v72, v72 row_ror:1 row_mask:0xf bank_mask:0xf bound_ctrl:1
	v_max_u32_dpp v42, v80, v80 row_ror:1 row_mask:0xf bank_mask:0xf bound_ctrl:1
	v_max_u32_dpp v44, v88, v88 row_ror:1 row_mask:0xf bank_mask:0xf bound_ctrl:1
	v_max_u32_dpp v43, v43, v43 row_ror:2 row_mask:0xf bank_mask:0xf bound_ctrl:1
	v_max_u32_dpp v45, v96, v96 row_ror:1 row_mask:0xf bank_mask:0xf bound_ctrl:1
	v_max_u32_dpp v42, v42, v42 row_ror:2 row_mask:0xf bank_mask:0xf bound_ctrl:1
	v_max_u32_dpp v44, v44, v44 row_ror:2 row_mask:0xf bank_mask:0xf bound_ctrl:1
	v_max_u32_dpp v43, v43, v43 row_ror:4 row_mask:0xf bank_mask:0xf bound_ctrl:1
	v_max_u32_dpp v45, v45, v45 row_ror:2 row_mask:0xf bank_mask:0xf bound_ctrl:1
	v_max_u32_dpp v42, v42, v42 row_ror:4 row_mask:0xf bank_mask:0xf bound_ctrl:1
	v_max_u32_dpp v44, v44, v44 row_ror:4 row_mask:0xf bank_mask:0xf bound_ctrl:1
	v_max_u32_dpp v43, v43, v43 row_ror:8 row_mask:0xf bank_mask:0xf bound_ctrl:1
	v_max_u32_dpp v45, v45, v45 row_ror:4 row_mask:0xf bank_mask:0xf bound_ctrl:1
	v_max_u32_dpp v42, v42, v42 row_ror:8 row_mask:0xf bank_mask:0xf bound_ctrl:1
	v_max_u32_dpp v44, v44, v44 row_ror:8 row_mask:0xf bank_mask:0xf bound_ctrl:1
	v_max_u32_dpp v45, v45, v45 row_ror:8 row_mask:0xf bank_mask:0xf bound_ctrl:1
	v_cmp_eq_u32_e64 s[84:85], v72, v43
	v_cmp_eq_u32_e64 s[86:87], v80, v42
	v_cmp_eq_u32_e64 s[88:89], v88, v44
	v_cmp_eq_u32_e64 s[90:91], v96, v45
	s_mov_b64 exec, s[84:85]
	v_pk_mov_b32 v[72:73], v[72:73], v[74:75] op_sel:[1,0] op_sel_hi:[1,0]
	v_pk_mov_b32 v[74:75], v[74:75], v[76:77] op_sel:[1,0] op_sel_hi:[1,0]
	v_pk_mov_b32 v[76:77], v[76:77], v[78:79] op_sel:[1,0] op_sel_hi:[1,0]
	v_pk_mov_b32 v[78:79], v[78:79], v[134:135] op_sel:[1,0] op_sel_hi:[1,0]
	s_mov_b64 exec, s[86:87]
	v_pk_mov_b32 v[80:81], v[80:81], v[82:83] op_sel:[1,0] op_sel_hi:[1,0]
	v_pk_mov_b32 v[82:83], v[82:83], v[84:85] op_sel:[1,0] op_sel_hi:[1,0]
	v_pk_mov_b32 v[84:85], v[84:85], v[86:87] op_sel:[1,0] op_sel_hi:[1,0]
	v_pk_mov_b32 v[86:87], v[86:87], v[134:135] op_sel:[1,0] op_sel_hi:[1,0]
	s_mov_b64 exec, s[88:89]
	v_pk_mov_b32 v[88:89], v[88:89], v[90:91] op_sel:[1,0] op_sel_hi:[1,0]
	v_pk_mov_b32 v[90:91], v[90:91], v[92:93] op_sel:[1,0] op_sel_hi:[1,0]
	v_pk_mov_b32 v[92:93], v[92:93], v[94:95] op_sel:[1,0] op_sel_hi:[1,0]
	v_pk_mov_b32 v[94:95], v[94:95], v[134:135] op_sel:[1,0] op_sel_hi:[1,0]
	s_mov_b64 exec, s[90:91]
	v_pk_mov_b32 v[96:97], v[96:97], v[98:99] op_sel:[1,0] op_sel_hi:[1,0]
	v_pk_mov_b32 v[98:99], v[98:99], v[100:101] op_sel:[1,0] op_sel_hi:[1,0]
	v_pk_mov_b32 v[100:101], v[100:101], v[102:103] op_sel:[1,0] op_sel_hi:[1,0]
	v_pk_mov_b32 v[102:103], v[102:103], v[134:135] op_sel:[1,0] op_sel_hi:[1,0]
	s_lshl_b64 exec, s[78:79], s40
	s_add_i32 s40, s40, 1
	v_pk_mov_b32 v[0:1], v[42:43], v[42:43] op_sel:[0,1] op_sel_hi:[0,1]
	v_pk_mov_b32 v[2:3], v[44:45], v[44:45] op_sel:[0,1] op_sel_hi:[0,1]
	s_mov_b64 exec, -1
	v_max_u32_dpp v43, v72, v72 row_ror:1 row_mask:0xf bank_mask:0xf bound_ctrl:1
	v_max_u32_dpp v42, v80, v80 row_ror:1 row_mask:0xf bank_mask:0xf bound_ctrl:1
	v_max_u32_dpp v44, v88, v88 row_ror:1 row_mask:0xf bank_mask:0xf bound_ctrl:1
	v_max_u32_dpp v43, v43, v43 row_ror:2 row_mask:0xf bank_mask:0xf bound_ctrl:1
	v_max_u32_dpp v45, v96, v96 row_ror:1 row_mask:0xf bank_mask:0xf bound_ctrl:1
	v_max_u32_dpp v42, v42, v42 row_ror:2 row_mask:0xf bank_mask:0xf bound_ctrl:1
	v_max_u32_dpp v44, v44, v44 row_ror:2 row_mask:0xf bank_mask:0xf bound_ctrl:1
	v_max_u32_dpp v43, v43, v43 row_ror:4 row_mask:0xf bank_mask:0xf bound_ctrl:1
	v_max_u32_dpp v45, v45, v45 row_ror:2 row_mask:0xf bank_mask:0xf bound_ctrl:1
	v_max_u32_dpp v42, v42, v42 row_ror:4 row_mask:0xf bank_mask:0xf bound_ctrl:1
	v_max_u32_dpp v44, v44, v44 row_ror:4 row_mask:0xf bank_mask:0xf bound_ctrl:1
	v_max_u32_dpp v43, v43, v43 row_ror:8 row_mask:0xf bank_mask:0xf bound_ctrl:1
	v_max_u32_dpp v45, v45, v45 row_ror:4 row_mask:0xf bank_mask:0xf bound_ctrl:1
	v_max_u32_dpp v42, v42, v42 row_ror:8 row_mask:0xf bank_mask:0xf bound_ctrl:1
	v_max_u32_dpp v44, v44, v44 row_ror:8 row_mask:0xf bank_mask:0xf bound_ctrl:1
	v_max_u32_dpp v45, v45, v45 row_ror:8 row_mask:0xf bank_mask:0xf bound_ctrl:1
	v_cmp_eq_u32_e64 s[84:85], v72, v43
	v_cmp_eq_u32_e64 s[86:87], v80, v42
	v_cmp_eq_u32_e64 s[88:89], v88, v44
	v_cmp_eq_u32_e64 s[90:91], v96, v45
	s_mov_b64 exec, s[84:85]
	v_pk_mov_b32 v[72:73], v[72:73], v[74:75] op_sel:[1,0] op_sel_hi:[1,0]
	v_pk_mov_b32 v[74:75], v[74:75], v[76:77] op_sel:[1,0] op_sel_hi:[1,0]
	v_pk_mov_b32 v[76:77], v[76:77], v[78:79] op_sel:[1,0] op_sel_hi:[1,0]
	s_mov_b64 exec, s[86:87]
	v_pk_mov_b32 v[80:81], v[80:81], v[82:83] op_sel:[1,0] op_sel_hi:[1,0]
	v_pk_mov_b32 v[82:83], v[82:83], v[84:85] op_sel:[1,0] op_sel_hi:[1,0]
	v_pk_mov_b32 v[84:85], v[84:85], v[86:87] op_sel:[1,0] op_sel_hi:[1,0]
	s_mov_b64 exec, s[88:89]
	v_pk_mov_b32 v[88:89], v[88:89], v[90:91] op_sel:[1,0] op_sel_hi:[1,0]
	v_pk_mov_b32 v[90:91], v[90:91], v[92:93] op_sel:[1,0] op_sel_hi:[1,0]
	v_pk_mov_b32 v[92:93], v[92:93], v[94:95] op_sel:[1,0] op_sel_hi:[1,0]
	s_mov_b64 exec, s[90:91]
	v_pk_mov_b32 v[96:97], v[96:97], v[98:99] op_sel:[1,0] op_sel_hi:[1,0]
	v_pk_mov_b32 v[98:99], v[98:99], v[100:101] op_sel:[1,0] op_sel_hi:[1,0]
	v_pk_mov_b32 v[100:101], v[100:101], v[102:103] op_sel:[1,0] op_sel_hi:[1,0]
	s_lshl_b64 exec, s[78:79], s40
	s_add_i32 s40, s40, 1
	v_pk_mov_b32 v[0:1], v[42:43], v[42:43] op_sel:[0,1] op_sel_hi:[0,1]
	v_pk_mov_b32 v[2:3], v[44:45], v[44:45] op_sel:[0,1] op_sel_hi:[0,1]
	s_mov_b64 exec, -1
	v_max_u32_dpp v43, v72, v72 row_ror:1 row_mask:0xf bank_mask:0xf bound_ctrl:1
	v_max_u32_dpp v42, v80, v80 row_ror:1 row_mask:0xf bank_mask:0xf bound_ctrl:1
	v_max_u32_dpp v44, v88, v88 row_ror:1 row_mask:0xf bank_mask:0xf bound_ctrl:1
	v_max_u32_dpp v43, v43, v43 row_ror:2 row_mask:0xf bank_mask:0xf bound_ctrl:1
	v_max_u32_dpp v45, v96, v96 row_ror:1 row_mask:0xf bank_mask:0xf bound_ctrl:1
	v_max_u32_dpp v42, v42, v42 row_ror:2 row_mask:0xf bank_mask:0xf bound_ctrl:1
	v_max_u32_dpp v44, v44, v44 row_ror:2 row_mask:0xf bank_mask:0xf bound_ctrl:1
	v_max_u32_dpp v43, v43, v43 row_ror:4 row_mask:0xf bank_mask:0xf bound_ctrl:1
	v_max_u32_dpp v45, v45, v45 row_ror:2 row_mask:0xf bank_mask:0xf bound_ctrl:1
	v_max_u32_dpp v42, v42, v42 row_ror:4 row_mask:0xf bank_mask:0xf bound_ctrl:1
	v_max_u32_dpp v44, v44, v44 row_ror:4 row_mask:0xf bank_mask:0xf bound_ctrl:1
	v_max_u32_dpp v43, v43, v43 row_ror:8 row_mask:0xf bank_mask:0xf bound_ctrl:1
	v_max_u32_dpp v45, v45, v45 row_ror:4 row_mask:0xf bank_mask:0xf bound_ctrl:1
	v_max_u32_dpp v42, v42, v42 row_ror:8 row_mask:0xf bank_mask:0xf bound_ctrl:1
	v_max_u32_dpp v44, v44, v44 row_ror:8 row_mask:0xf bank_mask:0xf bound_ctrl:1
	v_max_u32_dpp v45, v45, v45 row_ror:8 row_mask:0xf bank_mask:0xf bound_ctrl:1
	v_cmp_eq_u32_e64 s[84:85], v72, v43
	v_cmp_eq_u32_e64 s[86:87], v80, v42
	v_cmp_eq_u32_e64 s[88:89], v88, v44
	v_cmp_eq_u32_e64 s[90:91], v96, v45
	s_mov_b64 exec, s[84:85]
	v_pk_mov_b32 v[72:73], v[72:73], v[74:75] op_sel:[1,0] op_sel_hi:[1,0]
	v_pk_mov_b32 v[74:75], v[74:75], v[76:77] op_sel:[1,0] op_sel_hi:[1,0]
	v_pk_mov_b32 v[76:77], v[76:77], v[78:79] op_sel:[1,0] op_sel_hi:[1,0]
	s_mov_b64 exec, s[86:87]
	v_pk_mov_b32 v[80:81], v[80:81], v[82:83] op_sel:[1,0] op_sel_hi:[1,0]
	v_pk_mov_b32 v[82:83], v[82:83], v[84:85] op_sel:[1,0] op_sel_hi:[1,0]
	v_pk_mov_b32 v[84:85], v[84:85], v[86:87] op_sel:[1,0] op_sel_hi:[1,0]
	s_mov_b64 exec, s[88:89]
	v_pk_mov_b32 v[88:89], v[88:89], v[90:91] op_sel:[1,0] op_sel_hi:[1,0]
	v_pk_mov_b32 v[90:91], v[90:91], v[92:93] op_sel:[1,0] op_sel_hi:[1,0]
	v_pk_mov_b32 v[92:93], v[92:93], v[94:95] op_sel:[1,0] op_sel_hi:[1,0]
	s_mov_b64 exec, s[90:91]
	v_pk_mov_b32 v[96:97], v[96:97], v[98:99] op_sel:[1,0] op_sel_hi:[1,0]
	v_pk_mov_b32 v[98:99], v[98:99], v[100:101] op_sel:[1,0] op_sel_hi:[1,0]
	v_pk_mov_b32 v[100:101], v[100:101], v[102:103] op_sel:[1,0] op_sel_hi:[1,0]
	s_lshl_b64 exec, s[78:79], s40
	s_add_i32 s40, s40, 1
	v_pk_mov_b32 v[0:1], v[42:43], v[42:43] op_sel:[0,1] op_sel_hi:[0,1]
	v_pk_mov_b32 v[2:3], v[44:45], v[44:45] op_sel:[0,1] op_sel_hi:[0,1]
	s_mov_b64 exec, -1
	v_max_u32_dpp v43, v72, v72 row_ror:1 row_mask:0xf bank_mask:0xf bound_ctrl:1
	v_max_u32_dpp v42, v80, v80 row_ror:1 row_mask:0xf bank_mask:0xf bound_ctrl:1
	v_max_u32_dpp v44, v88, v88 row_ror:1 row_mask:0xf bank_mask:0xf bound_ctrl:1
	v_max_u32_dpp v43, v43, v43 row_ror:2 row_mask:0xf bank_mask:0xf bound_ctrl:1
	v_max_u32_dpp v45, v96, v96 row_ror:1 row_mask:0xf bank_mask:0xf bound_ctrl:1
	v_max_u32_dpp v42, v42, v42 row_ror:2 row_mask:0xf bank_mask:0xf bound_ctrl:1
	v_max_u32_dpp v44, v44, v44 row_ror:2 row_mask:0xf bank_mask:0xf bound_ctrl:1
	v_max_u32_dpp v43, v43, v43 row_ror:4 row_mask:0xf bank_mask:0xf bound_ctrl:1
	v_max_u32_dpp v45, v45, v45 row_ror:2 row_mask:0xf bank_mask:0xf bound_ctrl:1
	v_max_u32_dpp v42, v42, v42 row_ror:4 row_mask:0xf bank_mask:0xf bound_ctrl:1
	v_max_u32_dpp v44, v44, v44 row_ror:4 row_mask:0xf bank_mask:0xf bound_ctrl:1
	v_max_u32_dpp v43, v43, v43 row_ror:8 row_mask:0xf bank_mask:0xf bound_ctrl:1
	v_max_u32_dpp v45, v45, v45 row_ror:4 row_mask:0xf bank_mask:0xf bound_ctrl:1
	v_max_u32_dpp v42, v42, v42 row_ror:8 row_mask:0xf bank_mask:0xf bound_ctrl:1
	v_max_u32_dpp v44, v44, v44 row_ror:8 row_mask:0xf bank_mask:0xf bound_ctrl:1
	v_max_u32_dpp v45, v45, v45 row_ror:8 row_mask:0xf bank_mask:0xf bound_ctrl:1
	v_cmp_eq_u32_e64 s[84:85], v72, v43
	v_cmp_eq_u32_e64 s[86:87], v80, v42
	v_cmp_eq_u32_e64 s[88:89], v88, v44
	v_cmp_eq_u32_e64 s[90:91], v96, v45
	s_mov_b64 exec, s[84:85]
	v_pk_mov_b32 v[72:73], v[72:73], v[74:75] op_sel:[1,0] op_sel_hi:[1,0]
	v_pk_mov_b32 v[74:75], v[74:75], v[76:77] op_sel:[1,0] op_sel_hi:[1,0]
	s_mov_b64 exec, s[86:87]
	v_pk_mov_b32 v[80:81], v[80:81], v[82:83] op_sel:[1,0] op_sel_hi:[1,0]
	v_pk_mov_b32 v[82:83], v[82:83], v[84:85] op_sel:[1,0] op_sel_hi:[1,0]
	s_mov_b64 exec, s[88:89]
	v_pk_mov_b32 v[88:89], v[88:89], v[90:91] op_sel:[1,0] op_sel_hi:[1,0]
	v_pk_mov_b32 v[90:91], v[90:91], v[92:93] op_sel:[1,0] op_sel_hi:[1,0]
	s_mov_b64 exec, s[90:91]
	v_pk_mov_b32 v[96:97], v[96:97], v[98:99] op_sel:[1,0] op_sel_hi:[1,0]
	v_pk_mov_b32 v[98:99], v[98:99], v[100:101] op_sel:[1,0] op_sel_hi:[1,0]
	s_lshl_b64 exec, s[78:79], s40
	s_add_i32 s40, s40, 1
	v_pk_mov_b32 v[0:1], v[42:43], v[42:43] op_sel:[0,1] op_sel_hi:[0,1]
	v_pk_mov_b32 v[2:3], v[44:45], v[44:45] op_sel:[0,1] op_sel_hi:[0,1]
	s_mov_b64 exec, -1
	v_max_u32_dpp v43, v72, v72 row_ror:1 row_mask:0xf bank_mask:0xf bound_ctrl:1
	v_max_u32_dpp v42, v80, v80 row_ror:1 row_mask:0xf bank_mask:0xf bound_ctrl:1
	v_max_u32_dpp v44, v88, v88 row_ror:1 row_mask:0xf bank_mask:0xf bound_ctrl:1
	v_max_u32_dpp v43, v43, v43 row_ror:2 row_mask:0xf bank_mask:0xf bound_ctrl:1
	v_max_u32_dpp v45, v96, v96 row_ror:1 row_mask:0xf bank_mask:0xf bound_ctrl:1
	v_max_u32_dpp v42, v42, v42 row_ror:2 row_mask:0xf bank_mask:0xf bound_ctrl:1
	v_max_u32_dpp v44, v44, v44 row_ror:2 row_mask:0xf bank_mask:0xf bound_ctrl:1
	v_max_u32_dpp v43, v43, v43 row_ror:4 row_mask:0xf bank_mask:0xf bound_ctrl:1
	v_max_u32_dpp v45, v45, v45 row_ror:2 row_mask:0xf bank_mask:0xf bound_ctrl:1
	v_max_u32_dpp v42, v42, v42 row_ror:4 row_mask:0xf bank_mask:0xf bound_ctrl:1
	v_max_u32_dpp v44, v44, v44 row_ror:4 row_mask:0xf bank_mask:0xf bound_ctrl:1
	v_max_u32_dpp v43, v43, v43 row_ror:8 row_mask:0xf bank_mask:0xf bound_ctrl:1
	v_max_u32_dpp v45, v45, v45 row_ror:4 row_mask:0xf bank_mask:0xf bound_ctrl:1
	v_max_u32_dpp v42, v42, v42 row_ror:8 row_mask:0xf bank_mask:0xf bound_ctrl:1
	v_max_u32_dpp v44, v44, v44 row_ror:8 row_mask:0xf bank_mask:0xf bound_ctrl:1
	v_max_u32_dpp v45, v45, v45 row_ror:8 row_mask:0xf bank_mask:0xf bound_ctrl:1
	v_cmp_eq_u32_e64 s[84:85], v72, v43
	v_cmp_eq_u32_e64 s[86:87], v80, v42
	v_cmp_eq_u32_e64 s[88:89], v88, v44
	v_cmp_eq_u32_e64 s[90:91], v96, v45
	s_mov_b64 exec, s[84:85]
	v_pk_mov_b32 v[72:73], v[72:73], v[74:75] op_sel:[1,0] op_sel_hi:[1,0]
	v_pk_mov_b32 v[74:75], v[74:75], v[76:77] op_sel:[1,0] op_sel_hi:[1,0]
	s_mov_b64 exec, s[86:87]
	v_pk_mov_b32 v[80:81], v[80:81], v[82:83] op_sel:[1,0] op_sel_hi:[1,0]
	v_pk_mov_b32 v[82:83], v[82:83], v[84:85] op_sel:[1,0] op_sel_hi:[1,0]
	s_mov_b64 exec, s[88:89]
	v_pk_mov_b32 v[88:89], v[88:89], v[90:91] op_sel:[1,0] op_sel_hi:[1,0]
	v_pk_mov_b32 v[90:91], v[90:91], v[92:93] op_sel:[1,0] op_sel_hi:[1,0]
	s_mov_b64 exec, s[90:91]
	v_pk_mov_b32 v[96:97], v[96:97], v[98:99] op_sel:[1,0] op_sel_hi:[1,0]
	v_pk_mov_b32 v[98:99], v[98:99], v[100:101] op_sel:[1,0] op_sel_hi:[1,0]
	s_lshl_b64 exec, s[78:79], s40
	s_add_i32 s40, s40, 1
	v_pk_mov_b32 v[0:1], v[42:43], v[42:43] op_sel:[0,1] op_sel_hi:[0,1]
	v_pk_mov_b32 v[2:3], v[44:45], v[44:45] op_sel:[0,1] op_sel_hi:[0,1]
	s_mov_b64 exec, -1
	v_max_u32_dpp v43, v72, v72 row_ror:1 row_mask:0xf bank_mask:0xf bound_ctrl:1
	v_max_u32_dpp v42, v80, v80 row_ror:1 row_mask:0xf bank_mask:0xf bound_ctrl:1
	v_max_u32_dpp v44, v88, v88 row_ror:1 row_mask:0xf bank_mask:0xf bound_ctrl:1
	v_max_u32_dpp v43, v43, v43 row_ror:2 row_mask:0xf bank_mask:0xf bound_ctrl:1
	v_max_u32_dpp v45, v96, v96 row_ror:1 row_mask:0xf bank_mask:0xf bound_ctrl:1
	v_max_u32_dpp v42, v42, v42 row_ror:2 row_mask:0xf bank_mask:0xf bound_ctrl:1
	v_max_u32_dpp v44, v44, v44 row_ror:2 row_mask:0xf bank_mask:0xf bound_ctrl:1
	v_max_u32_dpp v43, v43, v43 row_ror:4 row_mask:0xf bank_mask:0xf bound_ctrl:1
	v_max_u32_dpp v45, v45, v45 row_ror:2 row_mask:0xf bank_mask:0xf bound_ctrl:1
	v_max_u32_dpp v42, v42, v42 row_ror:4 row_mask:0xf bank_mask:0xf bound_ctrl:1
	v_max_u32_dpp v44, v44, v44 row_ror:4 row_mask:0xf bank_mask:0xf bound_ctrl:1
	v_max_u32_dpp v43, v43, v43 row_ror:8 row_mask:0xf bank_mask:0xf bound_ctrl:1
	v_max_u32_dpp v45, v45, v45 row_ror:4 row_mask:0xf bank_mask:0xf bound_ctrl:1
	v_max_u32_dpp v42, v42, v42 row_ror:8 row_mask:0xf bank_mask:0xf bound_ctrl:1
	v_max_u32_dpp v44, v44, v44 row_ror:8 row_mask:0xf bank_mask:0xf bound_ctrl:1
	v_max_u32_dpp v45, v45, v45 row_ror:8 row_mask:0xf bank_mask:0xf bound_ctrl:1
	v_cmp_eq_u32_e64 s[84:85], v72, v43
	v_cmp_eq_u32_e64 s[86:87], v80, v42
	v_cmp_eq_u32_e64 s[88:89], v88, v44
	v_cmp_eq_u32_e64 s[90:91], v96, v45
	s_mov_b64 exec, s[84:85]
	v_pk_mov_b32 v[72:73], v[72:73], v[74:75] op_sel:[1,0] op_sel_hi:[1,0]
	s_mov_b64 exec, s[86:87]
	v_pk_mov_b32 v[80:81], v[80:81], v[82:83] op_sel:[1,0] op_sel_hi:[1,0]
	s_mov_b64 exec, s[88:89]
	v_pk_mov_b32 v[88:89], v[88:89], v[90:91] op_sel:[1,0] op_sel_hi:[1,0]
	s_mov_b64 exec, s[90:91]
	v_pk_mov_b32 v[96:97], v[96:97], v[98:99] op_sel:[1,0] op_sel_hi:[1,0]
	s_lshl_b64 exec, s[78:79], s40
	s_add_i32 s40, s40, 1
	v_pk_mov_b32 v[0:1], v[42:43], v[42:43] op_sel:[0,1] op_sel_hi:[0,1]
	v_pk_mov_b32 v[2:3], v[44:45], v[44:45] op_sel:[0,1] op_sel_hi:[0,1]
	s_mov_b64 exec, -1
	v_max_u32_dpp v43, v72, v72 row_ror:1 row_mask:0xf bank_mask:0xf bound_ctrl:1
	v_max_u32_dpp v42, v80, v80 row_ror:1 row_mask:0xf bank_mask:0xf bound_ctrl:1
	v_max_u32_dpp v44, v88, v88 row_ror:1 row_mask:0xf bank_mask:0xf bound_ctrl:1
	v_max_u32_dpp v43, v43, v43 row_ror:2 row_mask:0xf bank_mask:0xf bound_ctrl:1
	v_max_u32_dpp v45, v96, v96 row_ror:1 row_mask:0xf bank_mask:0xf bound_ctrl:1
	v_max_u32_dpp v42, v42, v42 row_ror:2 row_mask:0xf bank_mask:0xf bound_ctrl:1
	v_max_u32_dpp v44, v44, v44 row_ror:2 row_mask:0xf bank_mask:0xf bound_ctrl:1
	v_max_u32_dpp v43, v43, v43 row_ror:4 row_mask:0xf bank_mask:0xf bound_ctrl:1
	v_max_u32_dpp v45, v45, v45 row_ror:2 row_mask:0xf bank_mask:0xf bound_ctrl:1
	v_max_u32_dpp v42, v42, v42 row_ror:4 row_mask:0xf bank_mask:0xf bound_ctrl:1
	v_max_u32_dpp v44, v44, v44 row_ror:4 row_mask:0xf bank_mask:0xf bound_ctrl:1
	v_max_u32_dpp v43, v43, v43 row_ror:8 row_mask:0xf bank_mask:0xf bound_ctrl:1
	v_max_u32_dpp v45, v45, v45 row_ror:4 row_mask:0xf bank_mask:0xf bound_ctrl:1
	v_max_u32_dpp v42, v42, v42 row_ror:8 row_mask:0xf bank_mask:0xf bound_ctrl:1
	v_max_u32_dpp v44, v44, v44 row_ror:8 row_mask:0xf bank_mask:0xf bound_ctrl:1
	v_max_u32_dpp v45, v45, v45 row_ror:8 row_mask:0xf bank_mask:0xf bound_ctrl:1
	v_cmp_eq_u32_e64 s[84:85], v72, v43
	v_cmp_eq_u32_e64 s[86:87], v80, v42
	v_cmp_eq_u32_e64 s[88:89], v88, v44
	v_cmp_eq_u32_e64 s[90:91], v96, v45
	s_mov_b64 exec, s[84:85]
	v_pk_mov_b32 v[72:73], v[72:73], v[74:75] op_sel:[1,0] op_sel_hi:[1,0]
	s_mov_b64 exec, s[86:87]
	v_pk_mov_b32 v[80:81], v[80:81], v[82:83] op_sel:[1,0] op_sel_hi:[1,0]
	s_mov_b64 exec, s[88:89]
	v_pk_mov_b32 v[88:89], v[88:89], v[90:91] op_sel:[1,0] op_sel_hi:[1,0]
	s_mov_b64 exec, s[90:91]
	v_pk_mov_b32 v[96:97], v[96:97], v[98:99] op_sel:[1,0] op_sel_hi:[1,0]
	s_lshl_b64 exec, s[78:79], s40
	s_add_i32 s40, s40, 1
	v_pk_mov_b32 v[0:1], v[42:43], v[42:43] op_sel:[0,1] op_sel_hi:[0,1]
	v_pk_mov_b32 v[2:3], v[44:45], v[44:45] op_sel:[0,1] op_sel_hi:[0,1]
	s_mov_b64 exec, -1
	v_max_u32_dpp v43, v72, v72 row_ror:1 row_mask:0xf bank_mask:0xf bound_ctrl:1
	v_max_u32_dpp v42, v80, v80 row_ror:1 row_mask:0xf bank_mask:0xf bound_ctrl:1
	v_max_u32_dpp v44, v88, v88 row_ror:1 row_mask:0xf bank_mask:0xf bound_ctrl:1
	v_max_u32_dpp v43, v43, v43 row_ror:2 row_mask:0xf bank_mask:0xf bound_ctrl:1
	v_max_u32_dpp v45, v96, v96 row_ror:1 row_mask:0xf bank_mask:0xf bound_ctrl:1
	v_max_u32_dpp v42, v42, v42 row_ror:2 row_mask:0xf bank_mask:0xf bound_ctrl:1
	v_max_u32_dpp v44, v44, v44 row_ror:2 row_mask:0xf bank_mask:0xf bound_ctrl:1
	v_max_u32_dpp v43, v43, v43 row_ror:4 row_mask:0xf bank_mask:0xf bound_ctrl:1
	v_max_u32_dpp v45, v45, v45 row_ror:2 row_mask:0xf bank_mask:0xf bound_ctrl:1
	v_max_u32_dpp v42, v42, v42 row_ror:4 row_mask:0xf bank_mask:0xf bound_ctrl:1
	v_max_u32_dpp v44, v44, v44 row_ror:4 row_mask:0xf bank_mask:0xf bound_ctrl:1
	v_max_u32_dpp v43, v43, v43 row_ror:8 row_mask:0xf bank_mask:0xf bound_ctrl:1
	v_max_u32_dpp v45, v45, v45 row_ror:4 row_mask:0xf bank_mask:0xf bound_ctrl:1
	v_max_u32_dpp v42, v42, v42 row_ror:8 row_mask:0xf bank_mask:0xf bound_ctrl:1
	v_max_u32_dpp v44, v44, v44 row_ror:8 row_mask:0xf bank_mask:0xf bound_ctrl:1
	v_max_u32_dpp v45, v45, v45 row_ror:8 row_mask:0xf bank_mask:0xf bound_ctrl:1
	s_lshl_b64 exec, s[78:79], s40
	v_pk_mov_b32 v[0:1], v[42:43], v[42:43] op_sel:[0,1] op_sel_hi:[0,1]
	v_pk_mov_b32 v[2:3], v[44:45], v[44:45] op_sel:[0,1] op_sel_hi:[0,1]
	s_mov_b64 exec, -1
	v_cmp_lt_i32_e32 vcc, -1, v18
	v_mov_b32_e32 v6, 0
	v_mov_b32_e32 v7, 0
	v_cndmask_b32_e64 v4, v217, -1, vcc
	v_cmp_lt_i32_e32 vcc, -1, v0
	v_bitop3_b32 v8, v4, v18, s67 bitop3:0x78
	ds_bpermute_b32 v10, v198, v8
	v_cndmask_b32_e64 v4, v217, -1, vcc
	v_bitop3_b32 v9, v4, v0, s67 bitop3:0x78
	ds_bpermute_b32 v4, v196, v8
	ds_bpermute_b32 v5, v197, v9
	ds_bpermute_b32 v11, v199, v9
	s_and_saveexec_b64 s[0:1], s[6:7]
	s_cbranch_execz .LBB0_1352
	s_waitcnt lgkmcnt(0)
	v_add_f32_e32 v7, v10, v11
	v_cmp_lt_i32_e32 vcc, -1, v7
	s_nop 1
	v_cndmask_b32_e32 v10, -1, v217, vcc
	v_bitop3_b32 v7, v10, s59, v7 bitop3:0x48
	v_bitop3_b32 v7, v7, s54, v172 bitop3:0x36

.LBB0_1375:
	v_max_u32_dpp v31, v72, v72 row_ror:1 row_mask:0xf bank_mask:0xf bound_ctrl:1
	v_max_u32_dpp v30, v76, v76 row_ror:1 row_mask:0xf bank_mask:0xf bound_ctrl:1
	v_max_u32_dpp v32, v80, v80 row_ror:1 row_mask:0xf bank_mask:0xf bound_ctrl:1
	v_max_u32_dpp v31, v31, v31 row_ror:2 row_mask:0xf bank_mask:0xf bound_ctrl:1
	v_max_u32_dpp v33, v84, v84 row_ror:1 row_mask:0xf bank_mask:0xf bound_ctrl:1
	v_max_u32_dpp v30, v30, v30 row_ror:2 row_mask:0xf bank_mask:0xf bound_ctrl:1
	v_max_u32_dpp v32, v32, v32 row_ror:2 row_mask:0xf bank_mask:0xf bound_ctrl:1
	v_max_u32_dpp v31, v31, v31 row_ror:4 row_mask:0xf bank_mask:0xf bound_ctrl:1
	v_max_u32_dpp v33, v33, v33 row_ror:2 row_mask:0xf bank_mask:0xf bound_ctrl:1
	v_max_u32_dpp v30, v30, v30 row_ror:4 row_mask:0xf bank_mask:0xf bound_ctrl:1
	v_max_u32_dpp v32, v32, v32 row_ror:4 row_mask:0xf bank_mask:0xf bound_ctrl:1
	v_max_u32_dpp v31, v31, v31 row_ror:8 row_mask:0xf bank_mask:0xf bound_ctrl:1
	v_max_u32_dpp v33, v33, v33 row_ror:4 row_mask:0xf bank_mask:0xf bound_ctrl:1
	v_max_u32_dpp v30, v30, v30 row_ror:8 row_mask:0xf bank_mask:0xf bound_ctrl:1
	v_max_u32_dpp v32, v32, v32 row_ror:8 row_mask:0xf bank_mask:0xf bound_ctrl:1
	v_max_u32_dpp v33, v33, v33 row_ror:8 row_mask:0xf bank_mask:0xf bound_ctrl:1
	v_cmp_eq_u32_e64 s[84:85], v72, v31
	v_cmp_eq_u32_e64 s[86:87], v76, v30
	v_cmp_eq_u32_e64 s[88:89], v80, v32
	v_cmp_eq_u32_e64 s[90:91], v84, v33
	s_mov_b64 exec, s[84:85]
	v_pk_mov_b32 v[72:73], v[72:73], v[74:75] op_sel:[1,0] op_sel_hi:[1,0]
	v_pk_mov_b32 v[74:75], v[74:75], v[134:135] op_sel:[1,0] op_sel_hi:[1,0]
	s_mov_b64 exec, s[86:87]
	v_pk_mov_b32 v[76:77], v[76:77], v[78:79] op_sel:[1,0] op_sel_hi:[1,0]
	v_pk_mov_b32 v[78:79], v[78:79], v[134:135] op_sel:[1,0] op_sel_hi:[1,0]
	s_mov_b64 exec, s[88:89]
	v_pk_mov_b32 v[80:81], v[80:81], v[82:83] op_sel:[1,0] op_sel_hi:[1,0]
	v_pk_mov_b32 v[82:83], v[82:83], v[134:135] op_sel:[1,0] op_sel_hi:[1,0]
	s_mov_b64 exec, s[90:91]
	v_pk_mov_b32 v[84:85], v[84:85], v[86:87] op_sel:[1,0] op_sel_hi:[1,0]
	v_pk_mov_b32 v[86:87], v[86:87], v[134:135] op_sel:[1,0] op_sel_hi:[1,0]
	s_lshl_b64 exec, s[78:79], s40
	s_add_i32 s40, s40, 1
	v_pk_mov_b32 v[4:5], v[32:33], v[32:33] op_sel:[1,0] op_sel_hi:[1,0]
	v_pk_mov_b32 v[6:7], v[30:31], v[30:31] op_sel:[1,0] op_sel_hi:[1,0]
	s_mov_b64 exec, -1
	s_cmp_lg_u32 s40, 8
	s_cbranch_scc1 .LBB0_1375
	v_max_u32_dpp v31, v72, v72 row_ror:1 row_mask:0xf bank_mask:0xf bound_ctrl:1
	v_max_u32_dpp v30, v76, v76 row_ror:1 row_mask:0xf bank_mask:0xf bound_ctrl:1
	v_max_u32_dpp v32, v80, v80 row_ror:1 row_mask:0xf bank_mask:0xf bound_ctrl:1
	v_max_u32_dpp v31, v31, v31 row_ror:2 row_mask:0xf bank_mask:0xf bound_ctrl:1
	v_max_u32_dpp v33, v84, v84 row_ror:1 row_mask:0xf bank_mask:0xf bound_ctrl:1
	v_max_u32_dpp v30, v30, v30 row_ror:2 row_mask:0xf bank_mask:0xf bound_ctrl:1
	v_max_u32_dpp v32, v32, v32 row_ror:2 row_mask:0xf bank_mask:0xf bound_ctrl:1
	v_max_u32_dpp v31, v31, v31 row_ror:4 row_mask:0xf bank_mask:0xf bound_ctrl:1
	v_max_u32_dpp v33, v33, v33 row_ror:2 row_mask:0xf bank_mask:0xf bound_ctrl:1
	v_max_u32_dpp v30, v30, v30 row_ror:4 row_mask:0xf bank_mask:0xf bound_ctrl:1
	v_max_u32_dpp v32, v32, v32 row_ror:4 row_mask:0xf bank_mask:0xf bound_ctrl:1
	v_max_u32_dpp v31, v31, v31 row_ror:8 row_mask:0xf bank_mask:0xf bound_ctrl:1
	v_max_u32_dpp v33, v33, v33 row_ror:4 row_mask:0xf bank_mask:0xf bound_ctrl:1
	v_max_u32_dpp v30, v30, v30 row_ror:8 row_mask:0xf bank_mask:0xf bound_ctrl:1
	v_max_u32_dpp v32, v32, v32 row_ror:8 row_mask:0xf bank_mask:0xf bound_ctrl:1
	v_max_u32_dpp v33, v33, v33 row_ror:8 row_mask:0xf bank_mask:0xf bound_ctrl:1
	v_cmp_eq_u32_e64 s[84:85], v72, v31
	v_cmp_eq_u32_e64 s[86:87], v76, v30
	v_cmp_eq_u32_e64 s[88:89], v80, v32
	v_cmp_eq_u32_e64 s[90:91], v84, v33
	s_mov_b64 exec, s[84:85]
	v_pk_mov_b32 v[72:73], v[72:73], v[74:75] op_sel:[1,0] op_sel_hi:[1,0]
	v_pk_mov_b32 v[74:75], v[74:75], v[134:135] op_sel:[1,0] op_sel_hi:[1,0]
	s_mov_b64 exec, s[86:87]
	v_pk_mov_b32 v[76:77], v[76:77], v[78:79] op_sel:[1,0] op_sel_hi:[1,0]
	v_pk_mov_b32 v[78:79], v[78:79], v[134:135] op_sel:[1,0] op_sel_hi:[1,0]
	s_mov_b64 exec, s[88:89]
	v_pk_mov_b32 v[80:81], v[80:81], v[82:83] op_sel:[1,0] op_sel_hi:[1,0]
	v_pk_mov_b32 v[82:83], v[82:83], v[134:135] op_sel:[1,0] op_sel_hi:[1,0]
	s_mov_b64 exec, s[90:91]
	v_pk_mov_b32 v[84:85], v[84:85], v[86:87] op_sel:[1,0] op_sel_hi:[1,0]
	v_pk_mov_b32 v[86:87], v[86:87], v[134:135] op_sel:[1,0] op_sel_hi:[1,0]
	s_lshl_b64 exec, s[78:79], s40
	s_add_i32 s40, s40, 1
	v_pk_mov_b32 v[4:5], v[32:33], v[32:33] op_sel:[1,0] op_sel_hi:[1,0]
	v_pk_mov_b32 v[6:7], v[30:31], v[30:31] op_sel:[1,0] op_sel_hi:[1,0]
	s_mov_b64 exec, -1
	v_max_u32_dpp v31, v72, v72 row_ror:1 row_mask:0xf bank_mask:0xf bound_ctrl:1
	v_max_u32_dpp v30, v76, v76 row_ror:1 row_mask:0xf bank_mask:0xf bound_ctrl:1
	v_max_u32_dpp v32, v80, v80 row_ror:1 row_mask:0xf bank_mask:0xf bound_ctrl:1
	v_max_u32_dpp v31, v31, v31 row_ror:2 row_mask:0xf bank_mask:0xf bound_ctrl:1
	v_max_u32_dpp v33, v84, v84 row_ror:1 row_mask:0xf bank_mask:0xf bound_ctrl:1
	v_max_u32_dpp v30, v30, v30 row_ror:2 row_mask:0xf bank_mask:0xf bound_ctrl:1
	v_max_u32_dpp v32, v32, v32 row_ror:2 row_mask:0xf bank_mask:0xf bound_ctrl:1
	v_max_u32_dpp v31, v31, v31 row_ror:4 row_mask:0xf bank_mask:0xf bound_ctrl:1
	v_max_u32_dpp v33, v33, v33 row_ror:2 row_mask:0xf bank_mask:0xf bound_ctrl:1
	v_max_u32_dpp v30, v30, v30 row_ror:4 row_mask:0xf bank_mask:0xf bound_ctrl:1
	v_max_u32_dpp v32, v32, v32 row_ror:4 row_mask:0xf bank_mask:0xf bound_ctrl:1
	v_max_u32_dpp v31, v31, v31 row_ror:8 row_mask:0xf bank_mask:0xf bound_ctrl:1
	v_max_u32_dpp v33, v33, v33 row_ror:4 row_mask:0xf bank_mask:0xf bound_ctrl:1
	v_max_u32_dpp v30, v30, v30 row_ror:8 row_mask:0xf bank_mask:0xf bound_ctrl:1
	v_max_u32_dpp v32, v32, v32 row_ror:8 row_mask:0xf bank_mask:0xf bound_ctrl:1
	v_max_u32_dpp v33, v33, v33 row_ror:8 row_mask:0xf bank_mask:0xf bound_ctrl:1
	v_cmp_eq_u32_e64 s[84:85], v72, v31
	v_cmp_eq_u32_e64 s[86:87], v76, v30
	v_cmp_eq_u32_e64 s[88:89], v80, v32
	v_cmp_eq_u32_e64 s[90:91], v84, v33
	s_mov_b64 exec, s[84:85]
	v_pk_mov_b32 v[72:73], v[72:73], v[74:75] op_sel:[1,0] op_sel_hi:[1,0]
	v_pk_mov_b32 v[74:75], v[74:75], v[134:135] op_sel:[1,0] op_sel_hi:[1,0]
	s_mov_b64 exec, s[86:87]
	v_pk_mov_b32 v[76:77], v[76:77], v[78:79] op_sel:[1,0] op_sel_hi:[1,0]
	v_pk_mov_b32 v[78:79], v[78:79], v[134:135] op_sel:[1,0] op_sel_hi:[1,0]
	s_mov_b64 exec, s[88:89]
	v_pk_mov_b32 v[80:81], v[80:81], v[82:83] op_sel:[1,0] op_sel_hi:[1,0]
	v_pk_mov_b32 v[82:83], v[82:83], v[134:135] op_sel:[1,0] op_sel_hi:[1,0]
	s_mov_b64 exec, s[90:91]
	v_pk_mov_b32 v[84:85], v[84:85], v[86:87] op_sel:[1,0] op_sel_hi:[1,0]
	v_pk_mov_b32 v[86:87], v[86:87], v[134:135] op_sel:[1,0] op_sel_hi:[1,0]
	s_lshl_b64 exec, s[78:79], s40
	s_add_i32 s40, s40, 1
	v_pk_mov_b32 v[4:5], v[32:33], v[32:33] op_sel:[1,0] op_sel_hi:[1,0]
	v_pk_mov_b32 v[6:7], v[30:31], v[30:31] op_sel:[1,0] op_sel_hi:[1,0]
	s_mov_b64 exec, -1
	v_max_u32_dpp v31, v72, v72 row_ror:1 row_mask:0xf bank_mask:0xf bound_ctrl:1
	v_max_u32_dpp v30, v76, v76 row_ror:1 row_mask:0xf bank_mask:0xf bound_ctrl:1
	v_max_u32_dpp v32, v80, v80 row_ror:1 row_mask:0xf bank_mask:0xf bound_ctrl:1
	v_max_u32_dpp v31, v31, v31 row_ror:2 row_mask:0xf bank_mask:0xf bound_ctrl:1
	v_max_u32_dpp v33, v84, v84 row_ror:1 row_mask:0xf bank_mask:0xf bound_ctrl:1
	v_max_u32_dpp v30, v30, v30 row_ror:2 row_mask:0xf bank_mask:0xf bound_ctrl:1
	v_max_u32_dpp v32, v32, v32 row_ror:2 row_mask:0xf bank_mask:0xf bound_ctrl:1
	v_max_u32_dpp v31, v31, v31 row_ror:4 row_mask:0xf bank_mask:0xf bound_ctrl:1
	v_max_u32_dpp v33, v33, v33 row_ror:2 row_mask:0xf bank_mask:0xf bound_ctrl:1
	v_max_u32_dpp v30, v30, v30 row_ror:4 row_mask:0xf bank_mask:0xf bound_ctrl:1
	v_max_u32_dpp v32, v32, v32 row_ror:4 row_mask:0xf bank_mask:0xf bound_ctrl:1
	v_max_u32_dpp v31, v31, v31 row_ror:8 row_mask:0xf bank_mask:0xf bound_ctrl:1
	v_max_u32_dpp v33, v33, v33 row_ror:4 row_mask:0xf bank_mask:0xf bound_ctrl:1
	v_max_u32_dpp v30, v30, v30 row_ror:8 row_mask:0xf bank_mask:0xf bound_ctrl:1
	v_max_u32_dpp v32, v32, v32 row_ror:8 row_mask:0xf bank_mask:0xf bound_ctrl:1
	v_max_u32_dpp v33, v33, v33 row_ror:8 row_mask:0xf bank_mask:0xf bound_ctrl:1
	v_cmp_eq_u32_e64 s[84:85], v72, v31
	v_cmp_eq_u32_e64 s[86:87], v76, v30
	v_cmp_eq_u32_e64 s[88:89], v80, v32
	v_cmp_eq_u32_e64 s[90:91], v84, v33
	s_mov_b64 exec, s[84:85]
	v_pk_mov_b32 v[72:73], v[72:73], v[74:75] op_sel:[1,0] op_sel_hi:[1,0]
	v_pk_mov_b32 v[74:75], v[74:75], v[134:135] op_sel:[1,0] op_sel_hi:[1,0]
	s_mov_b64 exec, s[86:87]
	v_pk_mov_b32 v[76:77], v[76:77], v[78:79] op_sel:[1,0] op_sel_hi:[1,0]
	v_pk_mov_b32 v[78:79], v[78:79], v[134:135] op_sel:[1,0] op_sel_hi:[1,0]
	s_mov_b64 exec, s[88:89]
	v_pk_mov_b32 v[80:81], v[80:81], v[82:83] op_sel:[1,0] op_sel_hi:[1,0]
	v_pk_mov_b32 v[82:83], v[82:83], v[134:135] op_sel:[1,0] op_sel_hi:[1,0]
	s_mov_b64 exec, s[90:91]
	v_pk_mov_b32 v[84:85], v[84:85], v[86:87] op_sel:[1,0] op_sel_hi:[1,0]
	v_pk_mov_b32 v[86:87], v[86:87], v[134:135] op_sel:[1,0] op_sel_hi:[1,0]
	s_lshl_b64 exec, s[78:79], s40
	s_add_i32 s40, s40, 1
	v_pk_mov_b32 v[4:5], v[32:33], v[32:33] op_sel:[1,0] op_sel_hi:[1,0]
	v_pk_mov_b32 v[6:7], v[30:31], v[30:31] op_sel:[1,0] op_sel_hi:[1,0]
	s_mov_b64 exec, -1
	v_max_u32_dpp v31, v72, v72 row_ror:1 row_mask:0xf bank_mask:0xf bound_ctrl:1
	v_max_u32_dpp v30, v76, v76 row_ror:1 row_mask:0xf bank_mask:0xf bound_ctrl:1
	v_max_u32_dpp v32, v80, v80 row_ror:1 row_mask:0xf bank_mask:0xf bound_ctrl:1
	v_max_u32_dpp v31, v31, v31 row_ror:2 row_mask:0xf bank_mask:0xf bound_ctrl:1
	v_max_u32_dpp v33, v84, v84 row_ror:1 row_mask:0xf bank_mask:0xf bound_ctrl:1
	v_max_u32_dpp v30, v30, v30 row_ror:2 row_mask:0xf bank_mask:0xf bound_ctrl:1
	v_max_u32_dpp v32, v32, v32 row_ror:2 row_mask:0xf bank_mask:0xf bound_ctrl:1
	v_max_u32_dpp v31, v31, v31 row_ror:4 row_mask:0xf bank_mask:0xf bound_ctrl:1
	v_max_u32_dpp v33, v33, v33 row_ror:2 row_mask:0xf bank_mask:0xf bound_ctrl:1
	v_max_u32_dpp v30, v30, v30 row_ror:4 row_mask:0xf bank_mask:0xf bound_ctrl:1
	v_max_u32_dpp v32, v32, v32 row_ror:4 row_mask:0xf bank_mask:0xf bound_ctrl:1
	v_max_u32_dpp v31, v31, v31 row_ror:8 row_mask:0xf bank_mask:0xf bound_ctrl:1
	v_max_u32_dpp v33, v33, v33 row_ror:4 row_mask:0xf bank_mask:0xf bound_ctrl:1
	v_max_u32_dpp v30, v30, v30 row_ror:8 row_mask:0xf bank_mask:0xf bound_ctrl:1
	v_max_u32_dpp v32, v32, v32 row_ror:8 row_mask:0xf bank_mask:0xf bound_ctrl:1
	v_max_u32_dpp v33, v33, v33 row_ror:8 row_mask:0xf bank_mask:0xf bound_ctrl:1
	v_cmp_eq_u32_e64 s[84:85], v72, v31
	v_cmp_eq_u32_e64 s[86:87], v76, v30
	v_cmp_eq_u32_e64 s[88:89], v80, v32
	v_cmp_eq_u32_e64 s[90:91], v84, v33
	s_mov_b64 exec, s[84:85]
	v_pk_mov_b32 v[72:73], v[72:73], v[74:75] op_sel:[1,0] op_sel_hi:[1,0]
	v_pk_mov_b32 v[74:75], v[74:75], v[134:135] op_sel:[1,0] op_sel_hi:[1,0]
	s_mov_b64 exec, s[86:87]
	v_pk_mov_b32 v[76:77], v[76:77], v[78:79] op_sel:[1,0] op_sel_hi:[1,0]
	v_pk_mov_b32 v[78:79], v[78:79], v[134:135] op_sel:[1,0] op_sel_hi:[1,0]
	s_mov_b64 exec, s[88:89]
	v_pk_mov_b32 v[80:81], v[80:81], v[82:83] op_sel:[1,0] op_sel_hi:[1,0]
	v_pk_mov_b32 v[82:83], v[82:83], v[134:135] op_sel:[1,0] op_sel_hi:[1,0]
	s_mov_b64 exec, s[90:91]
	v_pk_mov_b32 v[84:85], v[84:85], v[86:87] op_sel:[1,0] op_sel_hi:[1,0]
	v_pk_mov_b32 v[86:87], v[86:87], v[134:135] op_sel:[1,0] op_sel_hi:[1,0]
	s_lshl_b64 exec, s[78:79], s40
	s_add_i32 s40, s40, 1
	v_pk_mov_b32 v[4:5], v[32:33], v[32:33] op_sel:[1,0] op_sel_hi:[1,0]
	v_pk_mov_b32 v[6:7], v[30:31], v[30:31] op_sel:[1,0] op_sel_hi:[1,0]
	s_mov_b64 exec, -1
	v_max_u32_dpp v31, v72, v72 row_ror:1 row_mask:0xf bank_mask:0xf bound_ctrl:1
	v_max_u32_dpp v30, v76, v76 row_ror:1 row_mask:0xf bank_mask:0xf bound_ctrl:1
	v_max_u32_dpp v32, v80, v80 row_ror:1 row_mask:0xf bank_mask:0xf bound_ctrl:1
	v_max_u32_dpp v31, v31, v31 row_ror:2 row_mask:0xf bank_mask:0xf bound_ctrl:1
	v_max_u32_dpp v33, v84, v84 row_ror:1 row_mask:0xf bank_mask:0xf bound_ctrl:1
	v_max_u32_dpp v30, v30, v30 row_ror:2 row_mask:0xf bank_mask:0xf bound_ctrl:1
	v_max_u32_dpp v32, v32, v32 row_ror:2 row_mask:0xf bank_mask:0xf bound_ctrl:1
	v_max_u32_dpp v31, v31, v31 row_ror:4 row_mask:0xf bank_mask:0xf bound_ctrl:1
	v_max_u32_dpp v33, v33, v33 row_ror:2 row_mask:0xf bank_mask:0xf bound_ctrl:1
	v_max_u32_dpp v30, v30, v30 row_ror:4 row_mask:0xf bank_mask:0xf bound_ctrl:1
	v_max_u32_dpp v32, v32, v32 row_ror:4 row_mask:0xf bank_mask:0xf bound_ctrl:1
	v_max_u32_dpp v31, v31, v31 row_ror:8 row_mask:0xf bank_mask:0xf bound_ctrl:1
	v_max_u32_dpp v33, v33, v33 row_ror:4 row_mask:0xf bank_mask:0xf bound_ctrl:1
	v_max_u32_dpp v30, v30, v30 row_ror:8 row_mask:0xf bank_mask:0xf bound_ctrl:1
	v_max_u32_dpp v32, v32, v32 row_ror:8 row_mask:0xf bank_mask:0xf bound_ctrl:1
	v_max_u32_dpp v33, v33, v33 row_ror:8 row_mask:0xf bank_mask:0xf bound_ctrl:1
	v_cmp_eq_u32_e64 s[84:85], v72, v31
	v_cmp_eq_u32_e64 s[86:87], v76, v30
	v_cmp_eq_u32_e64 s[88:89], v80, v32
	v_cmp_eq_u32_e64 s[90:91], v84, v33
	s_mov_b64 exec, s[84:85]
	v_pk_mov_b32 v[72:73], v[72:73], v[74:75] op_sel:[1,0] op_sel_hi:[1,0]
	v_pk_mov_b32 v[74:75], v[74:75], v[134:135] op_sel:[1,0] op_sel_hi:[1,0]
	s_mov_b64 exec, s[86:87]
	v_pk_mov_b32 v[76:77], v[76:77], v[78:79] op_sel:[1,0] op_sel_hi:[1,0]
	v_pk_mov_b32 v[78:79], v[78:79], v[134:135] op_sel:[1,0] op_sel_hi:[1,0]
	s_mov_b64 exec, s[88:89]
	v_pk_mov_b32 v[80:81], v[80:81], v[82:83] op_sel:[1,0] op_sel_hi:[1,0]
	v_pk_mov_b32 v[82:83], v[82:83], v[134:135] op_sel:[1,0] op_sel_hi:[1,0]
	s_mov_b64 exec, s[90:91]
	v_pk_mov_b32 v[84:85], v[84:85], v[86:87] op_sel:[1,0] op_sel_hi:[1,0]
	v_pk_mov_b32 v[86:87], v[86:87], v[134:135] op_sel:[1,0] op_sel_hi:[1,0]
	s_lshl_b64 exec, s[78:79], s40
	s_add_i32 s40, s40, 1
	v_pk_mov_b32 v[4:5], v[32:33], v[32:33] op_sel:[1,0] op_sel_hi:[1,0]
	v_pk_mov_b32 v[6:7], v[30:31], v[30:31] op_sel:[1,0] op_sel_hi:[1,0]
	s_mov_b64 exec, -1
	v_max_u32_dpp v31, v72, v72 row_ror:1 row_mask:0xf bank_mask:0xf bound_ctrl:1
	v_max_u32_dpp v30, v76, v76 row_ror:1 row_mask:0xf bank_mask:0xf bound_ctrl:1
	v_max_u32_dpp v32, v80, v80 row_ror:1 row_mask:0xf bank_mask:0xf bound_ctrl:1
	v_max_u32_dpp v31, v31, v31 row_ror:2 row_mask:0xf bank_mask:0xf bound_ctrl:1
	v_max_u32_dpp v33, v84, v84 row_ror:1 row_mask:0xf bank_mask:0xf bound_ctrl:1
	v_max_u32_dpp v30, v30, v30 row_ror:2 row_mask:0xf bank_mask:0xf bound_ctrl:1
	v_max_u32_dpp v32, v32, v32 row_ror:2 row_mask:0xf bank_mask:0xf bound_ctrl:1
	v_max_u32_dpp v31, v31, v31 row_ror:4 row_mask:0xf bank_mask:0xf bound_ctrl:1
	v_max_u32_dpp v33, v33, v33 row_ror:2 row_mask:0xf bank_mask:0xf bound_ctrl:1
	v_max_u32_dpp v30, v30, v30 row_ror:4 row_mask:0xf bank_mask:0xf bound_ctrl:1
	v_max_u32_dpp v32, v32, v32 row_ror:4 row_mask:0xf bank_mask:0xf bound_ctrl:1
	v_max_u32_dpp v31, v31, v31 row_ror:8 row_mask:0xf bank_mask:0xf bound_ctrl:1
	v_max_u32_dpp v33, v33, v33 row_ror:4 row_mask:0xf bank_mask:0xf bound_ctrl:1
	v_max_u32_dpp v30, v30, v30 row_ror:8 row_mask:0xf bank_mask:0xf bound_ctrl:1
	v_max_u32_dpp v32, v32, v32 row_ror:8 row_mask:0xf bank_mask:0xf bound_ctrl:1
	v_max_u32_dpp v33, v33, v33 row_ror:8 row_mask:0xf bank_mask:0xf bound_ctrl:1
	v_cmp_eq_u32_e64 s[84:85], v72, v31
	v_cmp_eq_u32_e64 s[86:87], v76, v30
	v_cmp_eq_u32_e64 s[88:89], v80, v32
	v_cmp_eq_u32_e64 s[90:91], v84, v33
	s_mov_b64 exec, s[84:85]
	v_pk_mov_b32 v[72:73], v[72:73], v[74:75] op_sel:[1,0] op_sel_hi:[1,0]
	s_mov_b64 exec, s[86:87]
	v_pk_mov_b32 v[76:77], v[76:77], v[78:79] op_sel:[1,0] op_sel_hi:[1,0]
	s_mov_b64 exec, s[88:89]
	v_pk_mov_b32 v[80:81], v[80:81], v[82:83] op_sel:[1,0] op_sel_hi:[1,0]
	s_mov_b64 exec, s[90:91]
	v_pk_mov_b32 v[84:85], v[84:85], v[86:87] op_sel:[1,0] op_sel_hi:[1,0]
	s_lshl_b64 exec, s[78:79], s40
	s_add_i32 s40, s40, 1
	v_pk_mov_b32 v[4:5], v[32:33], v[32:33] op_sel:[1,0] op_sel_hi:[1,0]
	v_pk_mov_b32 v[6:7], v[30:31], v[30:31] op_sel:[1,0] op_sel_hi:[1,0]
	s_mov_b64 exec, -1
	v_max_u32_dpp v31, v72, v72 row_ror:1 row_mask:0xf bank_mask:0xf bound_ctrl:1
	v_max_u32_dpp v30, v76, v76 row_ror:1 row_mask:0xf bank_mask:0xf bound_ctrl:1
	v_max_u32_dpp v32, v80, v80 row_ror:1 row_mask:0xf bank_mask:0xf bound_ctrl:1
	v_max_u32_dpp v31, v31, v31 row_ror:2 row_mask:0xf bank_mask:0xf bound_ctrl:1
	v_max_u32_dpp v33, v84, v84 row_ror:1 row_mask:0xf bank_mask:0xf bound_ctrl:1
	v_max_u32_dpp v30, v30, v30 row_ror:2 row_mask:0xf bank_mask:0xf bound_ctrl:1
	v_max_u32_dpp v32, v32, v32 row_ror:2 row_mask:0xf bank_mask:0xf bound_ctrl:1
	v_max_u32_dpp v31, v31, v31 row_ror:4 row_mask:0xf bank_mask:0xf bound_ctrl:1
	v_max_u32_dpp v33, v33, v33 row_ror:2 row_mask:0xf bank_mask:0xf bound_ctrl:1
	v_max_u32_dpp v30, v30, v30 row_ror:4 row_mask:0xf bank_mask:0xf bound_ctrl:1
	v_max_u32_dpp v32, v32, v32 row_ror:4 row_mask:0xf bank_mask:0xf bound_ctrl:1
	v_max_u32_dpp v31, v31, v31 row_ror:8 row_mask:0xf bank_mask:0xf bound_ctrl:1
	v_max_u32_dpp v33, v33, v33 row_ror:4 row_mask:0xf bank_mask:0xf bound_ctrl:1
	v_max_u32_dpp v30, v30, v30 row_ror:8 row_mask:0xf bank_mask:0xf bound_ctrl:1
	v_max_u32_dpp v32, v32, v32 row_ror:8 row_mask:0xf bank_mask:0xf bound_ctrl:1
	v_max_u32_dpp v33, v33, v33 row_ror:8 row_mask:0xf bank_mask:0xf bound_ctrl:1
	v_cmp_eq_u32_e64 s[84:85], v72, v31
	v_cmp_eq_u32_e64 s[86:87], v76, v30
	v_cmp_eq_u32_e64 s[88:89], v80, v32
	v_cmp_eq_u32_e64 s[90:91], v84, v33
	s_mov_b64 exec, s[84:85]
	v_pk_mov_b32 v[72:73], v[72:73], v[74:75] op_sel:[1,0] op_sel_hi:[1,0]
	s_mov_b64 exec, s[86:87]
	v_pk_mov_b32 v[76:77], v[76:77], v[78:79] op_sel:[1,0] op_sel_hi:[1,0]
	s_mov_b64 exec, s[88:89]
	v_pk_mov_b32 v[80:81], v[80:81], v[82:83] op_sel:[1,0] op_sel_hi:[1,0]
	s_mov_b64 exec, s[90:91]
	v_pk_mov_b32 v[84:85], v[84:85], v[86:87] op_sel:[1,0] op_sel_hi:[1,0]
	s_lshl_b64 exec, s[78:79], s40
	s_add_i32 s40, s40, 1
	v_pk_mov_b32 v[4:5], v[32:33], v[32:33] op_sel:[1,0] op_sel_hi:[1,0]
	v_pk_mov_b32 v[6:7], v[30:31], v[30:31] op_sel:[1,0] op_sel_hi:[1,0]
	s_mov_b64 exec, -1
	v_max_u32_dpp v31, v72, v72 row_ror:1 row_mask:0xf bank_mask:0xf bound_ctrl:1
	v_max_u32_dpp v30, v76, v76 row_ror:1 row_mask:0xf bank_mask:0xf bound_ctrl:1
	v_max_u32_dpp v32, v80, v80 row_ror:1 row_mask:0xf bank_mask:0xf bound_ctrl:1
	v_max_u32_dpp v31, v31, v31 row_ror:2 row_mask:0xf bank_mask:0xf bound_ctrl:1
	v_max_u32_dpp v33, v84, v84 row_ror:1 row_mask:0xf bank_mask:0xf bound_ctrl:1
	v_max_u32_dpp v30, v30, v30 row_ror:2 row_mask:0xf bank_mask:0xf bound_ctrl:1
	v_max_u32_dpp v32, v32, v32 row_ror:2 row_mask:0xf bank_mask:0xf bound_ctrl:1
	v_max_u32_dpp v31, v31, v31 row_ror:4 row_mask:0xf bank_mask:0xf bound_ctrl:1
	v_max_u32_dpp v33, v33, v33 row_ror:2 row_mask:0xf bank_mask:0xf bound_ctrl:1
	v_max_u32_dpp v30, v30, v30 row_ror:4 row_mask:0xf bank_mask:0xf bound_ctrl:1
	v_max_u32_dpp v32, v32, v32 row_ror:4 row_mask:0xf bank_mask:0xf bound_ctrl:1
	v_max_u32_dpp v31, v31, v31 row_ror:8 row_mask:0xf bank_mask:0xf bound_ctrl:1
	v_max_u32_dpp v33, v33, v33 row_ror:4 row_mask:0xf bank_mask:0xf bound_ctrl:1
	v_max_u32_dpp v30, v30, v30 row_ror:8 row_mask:0xf bank_mask:0xf bound_ctrl:1
	v_max_u32_dpp v32, v32, v32 row_ror:8 row_mask:0xf bank_mask:0xf bound_ctrl:1
	v_max_u32_dpp v33, v33, v33 row_ror:8 row_mask:0xf bank_mask:0xf bound_ctrl:1
	s_lshl_b64 exec, s[78:79], s40
	v_pk_mov_b32 v[4:5], v[32:33], v[32:33] op_sel:[1,0] op_sel_hi:[1,0]
	v_pk_mov_b32 v[6:7], v[30:31], v[30:31] op_sel:[1,0] op_sel_hi:[1,0]
	s_mov_b64 exec, -1
	v_max_u32_dpp v15, v7, v7 row_ror:1 row_mask:0xf bank_mask:0xf bound_ctrl:1
	v_cmp_lt_i32_e32 vcc, -1, v7
	v_bitop3_b32 v11, v18, s60, v18 bitop3:0xc
	v_max_u32_dpp v15, v15, v15 row_ror:2 row_mask:0xf bank_mask:0xf bound_ctrl:1
	v_cndmask_b32_e64 v14, v217, -1, vcc
	v_bitop3_b32 v14, v14, v7, s59 bitop3:0x78
	v_max_u32_dpp v15, v15, v15 row_ror:4 row_mask:0xf bank_mask:0xf bound_ctrl:1
	v_not_b32_e32 v13, v7
	v_lshrrev_b32_e32 v13, 4, v13
	v_max_u32_dpp v15, v15, v15 row_ror:8 row_mask:0xf bank_mask:0xf bound_ctrl:1
	v_cmp_lt_i32_e32 vcc, -1, v15
	v_and_or_b32 v13, v13, 15, v195
	v_lshlrev_b32_e32 v13, 2, v13
	v_cndmask_b32_e64 v18, v217, -1, vcc
	v_bitop3_b32 v15, v18, v15, s59 bitop3:0x78
	v_sub_f32_e32 v14, v14, v15
	v_mul_f32_e32 v14, 0x3fb8aa3b, v14
	v_exp_f32_e32 v14, v14
	ds_bpermute_b32 v11, v13, v11
	v_bitop3_b32 v7, v7, v195, 15 bitop3:0xce
	v_bitop3_b32 v0, v0, s60, v0 bitop3:0xc
	v_add_f32_dpp v13, v14, v14 row_ror:1 row_mask:0xf bank_mask:0xf bound_ctrl:1
	v_lshlrev_b32_e32 v7, 2, v7
	ds_bpermute_b32 v0, v7, v0
	v_add_f32_dpp v13, v13, v13 row_ror:2 row_mask:0xf bank_mask:0xf bound_ctrl:1
	v_bitop3_b32 v10, v19, s60, v19 bitop3:0xc
	v_bitop3_b32 v9, v20, s60, v20 bitop3:0xc
	v_add_f32_dpp v13, v13, v13 row_ror:4 row_mask:0xf bank_mask:0xf bound_ctrl:1
	v_lshl_or_b32 v12, s33, 4, v171
	s_waitcnt lgkmcnt(0)
	v_lshl_add_u32 v0, v11, 7, v0
	v_add_f32_dpp v13, v13, v13 row_ror:8 row_mask:0xf bank_mask:0xf bound_ctrl:1
	v_div_scale_f32 v15, s[0:1], v13, v13, v14
	v_rcp_f32_e32 v18, v15
	v_bitop3_b32 v1, v1, s60, v1 bitop3:0xc
	v_bitop3_b32 v2, v2, s60, v2 bitop3:0xc
	v_bitop3_b32 v3, v3, s60, v3 bitop3:0xc
	v_fma_f32 v7, -v15, v18, 1.0
	v_fmac_f32_e32 v18, v7, v18
	v_div_scale_f32 v7, vcc, v14, v13, v14
	v_mul_f32_e32 v19, v7, v18
	v_fma_f32 v20, -v15, v19, v7
	v_fmac_f32_e32 v19, v20, v18
	v_fma_f32 v7, -v15, v19, v7
	v_div_fmas_f32 v7, v7, v18, v19
	v_div_fixup_f32 v7, v7, v13, v14
	v_or_b32_e32 v13, v12, v183
	v_lshl_add_u32 v11, v13, 1, s63
	v_cvt_f16_f32_e32 v7, v7
	v_max_u32_dpp v13, v6, v6 row_ror:1 row_mask:0xf bank_mask:0xf bound_ctrl:1
	v_cmp_lt_i32_e32 vcc, -1, v6
	ds_write_b16 v11, v0
	ds_write_b16 v11, v7 offset:32768
	v_max_u32_dpp v13, v13, v13 row_ror:2 row_mask:0xf bank_mask:0xf bound_ctrl:1
	v_cndmask_b32_e64 v7, v217, -1, vcc
	v_bitop3_b32 v7, v7, v6, s59 bitop3:0x78
	v_max_u32_dpp v13, v13, v13 row_ror:4 row_mask:0xf bank_mask:0xf bound_ctrl:1
	v_not_b32_e32 v0, v6
	v_lshrrev_b32_e32 v0, 4, v0
	v_max_u32_dpp v13, v13, v13 row_ror:8 row_mask:0xf bank_mask:0xf bound_ctrl:1
	v_cmp_lt_i32_e32 vcc, -1, v13
	v_and_or_b32 v0, v0, 15, v195
	v_lshlrev_b32_e32 v0, 2, v0
	v_cndmask_b32_e64 v14, v217, -1, vcc
	v_bitop3_b32 v13, v14, v13, s59 bitop3:0x78
	v_sub_f32_e32 v7, v7, v13
	v_mul_f32_e32 v7, 0x3fb8aa3b, v7
	v_exp_f32_e32 v7, v7
	ds_bpermute_b32 v0, v0, v10
	v_bitop3_b32 v6, v6, v195, 15 bitop3:0xce
	v_lshlrev_b32_e32 v6, 2, v6
	v_add_f32_dpp v10, v7, v7 row_ror:1 row_mask:0xf bank_mask:0xf bound_ctrl:1
	ds_bpermute_b32 v1, v6, v1
	v_bitop3_b32 v8, v21, s60, v21 bitop3:0xc
	v_add_f32_dpp v10, v10, v10 row_ror:2 row_mask:0xf bank_mask:0xf bound_ctrl:1
	s_waitcnt lgkmcnt(0)
	v_lshl_add_u32 v0, v0, 7, v1
	v_add_f32_dpp v10, v10, v10 row_ror:4 row_mask:0xf bank_mask:0xf bound_ctrl:1
	ds_write_b16 v11, v0 offset:256
	v_not_b32_e32 v1, v5
	v_add_f32_dpp v10, v10, v10 row_ror:8 row_mask:0xf bank_mask:0xf bound_ctrl:1
	v_div_scale_f32 v13, s[0:1], v10, v10, v7
	v_rcp_f32_e32 v14, v13
	v_lshrrev_b32_e32 v1, 4, v1
	v_and_or_b32 v1, v1, 15, v195
	v_lshlrev_b32_e32 v1, 2, v1
	v_fma_f32 v6, -v13, v14, 1.0
	v_fmac_f32_e32 v14, v6, v14
	v_div_scale_f32 v6, vcc, v7, v10, v7
	v_mul_f32_e32 v15, v6, v14
	v_fma_f32 v18, -v13, v15, v6
	v_fmac_f32_e32 v15, v18, v14
	v_fma_f32 v6, -v13, v15, v6
	v_div_fmas_f32 v6, v6, v14, v15
	v_div_fixup_f32 v6, v6, v10, v7
	v_max_u32_dpp v7, v5, v5 row_ror:1 row_mask:0xf bank_mask:0xf bound_ctrl:1
	v_cmp_lt_i32_e32 vcc, -1, v5
	v_cvt_f16_f32_e32 v0, v6
	v_max_u32_dpp v7, v7, v7 row_ror:2 row_mask:0xf bank_mask:0xf bound_ctrl:1
	v_cndmask_b32_e64 v6, v217, -1, vcc
	v_bitop3_b32 v6, v6, v5, s59 bitop3:0x78
	v_max_u32_dpp v7, v7, v7 row_ror:4 row_mask:0xf bank_mask:0xf bound_ctrl:1
	ds_bpermute_b32 v1, v1, v9
	v_bitop3_b32 v5, v5, v195, 15 bitop3:0xce
	v_max_u32_dpp v7, v7, v7 row_ror:8 row_mask:0xf bank_mask:0xf bound_ctrl:1
	v_cmp_lt_i32_e32 vcc, -1, v7
	v_lshlrev_b32_e32 v5, 2, v5
	ds_bpermute_b32 v2, v5, v2
	v_cndmask_b32_e64 v10, v217, -1, vcc
	v_bitop3_b32 v7, v10, v7, s59 bitop3:0x78
	v_sub_f32_e32 v6, v6, v7
	v_mul_f32_e32 v6, 0x3fb8aa3b, v6
	v_exp_f32_e32 v6, v6
	ds_write_b16 v11, v0 offset:33024
	s_waitcnt lgkmcnt(1)
	v_lshl_add_u32 v0, v1, 7, v2
	v_max_u32_dpp v2, v4, v4 row_ror:1 row_mask:0xf bank_mask:0xf bound_ctrl:1
	v_add_f32_dpp v7, v6, v6 row_ror:1 row_mask:0xf bank_mask:0xf bound_ctrl:1
	s_nop 0
	v_max_u32_dpp v2, v2, v2 row_ror:2 row_mask:0xf bank_mask:0xf bound_ctrl:1
	v_add_f32_dpp v7, v7, v7 row_ror:2 row_mask:0xf bank_mask:0xf bound_ctrl:1
	s_nop 0
	v_max_u32_dpp v2, v2, v2 row_ror:4 row_mask:0xf bank_mask:0xf bound_ctrl:1
	v_add_f32_dpp v7, v7, v7 row_ror:4 row_mask:0xf bank_mask:0xf bound_ctrl:1
	s_nop 0
	v_max_u32_dpp v2, v2, v2 row_ror:8 row_mask:0xf bank_mask:0xf bound_ctrl:1
	v_add_f32_dpp v7, v7, v7 row_ror:8 row_mask:0xf bank_mask:0xf bound_ctrl:1
	v_div_scale_f32 v9, s[0:1], v7, v7, v6
	v_rcp_f32_e32 v10, v9
	s_nop 0
	v_fma_f32 v5, -v9, v10, 1.0
	v_fmac_f32_e32 v10, v5, v10
	v_div_scale_f32 v5, vcc, v6, v7, v6
	v_mul_f32_e32 v13, v5, v10
	v_fma_f32 v14, -v9, v13, v5
	v_fmac_f32_e32 v13, v14, v10
	v_fma_f32 v5, -v9, v13, v5
	v_div_fmas_f32 v5, v5, v10, v13
	v_div_fixup_f32 v5, v5, v7, v6
	v_cvt_f16_f32_e32 v5, v5
	v_cmp_lt_i32_e32 vcc, -1, v4
	ds_write_b16 v11, v0 offset:512
	ds_write_b16 v11, v5 offset:33280
	v_cndmask_b32_e64 v1, v217, -1, vcc
	v_cmp_lt_i32_e32 vcc, -1, v2
	v_bitop3_b32 v1, v1, v4, s59 bitop3:0x78
	v_not_b32_e32 v0, v4
	v_cndmask_b32_e64 v5, v217, -1, vcc
	v_bitop3_b32 v2, v5, v2, s59 bitop3:0x78
	v_sub_f32_e32 v1, v1, v2
	v_mul_f32_e32 v1, 0x3fb8aa3b, v1
	v_exp_f32_e32 v1, v1
	v_bitop3_b32 v4, v4, v195, 15 bitop3:0xce
	v_lshlrev_b32_e32 v4, 2, v4
	v_lshrrev_b32_e32 v0, 4, v0
	v_add_f32_dpp v2, v1, v1 row_ror:1 row_mask:0xf bank_mask:0xf bound_ctrl:1
	ds_bpermute_b32 v3, v4, v3
	v_and_or_b32 v0, v0, 15, v195
	v_add_f32_dpp v2, v2, v2 row_ror:2 row_mask:0xf bank_mask:0xf bound_ctrl:1
	v_lshlrev_b32_e32 v0, 2, v0
	ds_bpermute_b32 v0, v0, v8
	v_add_f32_dpp v2, v2, v2 row_ror:4 row_mask:0xf bank_mask:0xf bound_ctrl:1
	s_waitcnt lgkmcnt(0)
	v_lshl_add_u32 v0, v0, 7, v3
	v_add_f32_dpp v2, v2, v2 row_ror:8 row_mask:0xf bank_mask:0xf bound_ctrl:1
	v_div_scale_f32 v5, s[0:1], v2, v2, v1
	v_rcp_f32_e32 v6, v5
	s_add_i32 s0, s33, 1
	s_cmp_lg_u32 s33, 7
	s_cselect_b32 s1, s0, 7
	v_fma_f32 v4, -v5, v6, 1.0
	v_fmac_f32_e32 v6, v4, v6
	v_div_scale_f32 v4, vcc, v1, v2, v1
	v_mul_f32_e32 v7, v4, v6
	v_fma_f32 v8, -v5, v7, v4
	v_fmac_f32_e32 v7, v8, v6
	v_fma_f32 v4, -v5, v7, v4
	v_div_fmas_f32 v4, v4, v6, v7
	v_div_fixup_f32 v1, v4, v2, v1
	v_add_u32_e32 v2, v12, v182
	v_cvt_f16_f32_e32 v1, v1
	v_lshl_or_b32 v2, v2, 1, v218
	s_lshl_b32 s40, s1, 16
	v_add_u32_e32 v2, s63, v2
	s_cmp_lt_u32 s1, 4
	ds_write_b16 v2, v0
	ds_write_b16 v2, v1 offset:32768
	v_lshl_add_u64 v[0:1], v[154:155], 0, s[40:41]
	s_cselect_b32 s33, s3, s56
	s_cselect_b32 s40, s2, s55
	v_mov_b32_e32 v2, s40
	v_mov_b32_e32 v3, s33
	s_lshl_b32 s1, s1, 9
	v_lshl_add_u64 v[2:3], v[16:17], 1, v[2:3]
	s_and_b32 s40, s1, 0x600
	v_lshl_add_u64 v[2:3], v[2:3], 0, s[40:41]
	v_lshl_add_u64 v[12:13], v[2:3], 0, v[148:149]
	s_cmp_eq_u32 s0, 8
	s_mov_b32 s33, s0
	s_cbranch_scc0 .LBB0_1346
	s_waitcnt lgkmcnt(0)
	s_barrier
	ds_read_b128 v[0:3], v185
	ds_read_b128 v[40:43], v185 offset:16
	s_ashr_i32 s49, s48, 31
	s_lshl_b64 s[0:1], s[48:49], 10
	v_lshl_add_u64 v[144:145], v[152:153], 0, s[0:1]
	s_waitcnt lgkmcnt(1)
	v_lshlrev_b32_e32 v4, 7, v0
	v_bfe_u32 v0, v0, 16, 16
	v_and_or_b32 v64, v4, s68, v150
	v_lshl_or_b32 v0, v0, 7, v150
	v_lshlrev_b32_e32 v4, 7, v1
	v_and_or_b32 v4, v4, s68, v150
	global_load_dwordx4 v[60:63], v0, s[26:27]
	global_load_dwordx4 v[56:59], v4, s[26:27]
	v_bfe_u32 v0, v1, 16, 16
	v_lshl_or_b32 v0, v0, 7, v150
	v_lshlrev_b32_e32 v1, 7, v2
	v_and_or_b32 v1, v1, s68, v150
	global_load_dwordx4 v[52:55], v0, s[26:27]
	global_load_dwordx4 v[48:51], v1, s[26:27]
	v_bfe_u32 v0, v2, 16, 16
	v_lshl_or_b32 v0, v0, 7, v150
	v_lshlrev_b32_e32 v1, 7, v3
	v_and_or_b32 v1, v1, s68, v150
	global_load_dwordx4 v[44:47], v0, s[26:27]
	global_load_dwordx4 v[36:39], v1, s[26:27]
	v_bfe_u32 v0, v3, 16, 16
	v_lshl_or_b32 v0, v0, 7, v150
	s_waitcnt lgkmcnt(0)
	v_lshlrev_b32_e32 v1, 7, v40
	v_and_or_b32 v1, v1, s68, v150
	global_load_dwordx4 v[32:35], v0, s[26:27]
	global_load_dwordx4 v[28:31], v1, s[26:27]
	v_bfe_u32 v0, v40, 16, 16
	v_lshl_or_b32 v0, v0, 7, v150
	v_lshlrev_b32_e32 v1, 7, v41
	v_and_or_b32 v1, v1, s68, v150
	global_load_dwordx4 v[24:27], v0, s[26:27]
	global_load_dwordx4 v[20:23], v1, s[26:27]
	v_bfe_u32 v0, v41, 16, 16
	v_lshl_or_b32 v0, v0, 7, v150
	v_lshlrev_b32_e32 v1, 7, v42
	v_and_or_b32 v1, v1, s68, v150
	global_load_dwordx4 v[16:19], v0, s[26:27]
	global_load_dwordx4 v[12:15], v1, s[26:27]
	v_bfe_u32 v0, v42, 16, 16
	v_lshl_or_b32 v0, v0, 7, v150
	v_lshlrev_b32_e32 v1, 7, v43
	v_and_or_b32 v1, v1, s68, v150
	global_load_dwordx4 v[8:11], v0, s[26:27]
	global_load_dwordx4 v[4:7], v1, s[26:27]
	v_bfe_u32 v0, v43, 16, 16
	v_lshl_or_b32 v0, v0, 7, v150
	global_load_dwordx4 v[0:3], v0, s[26:27]
	s_nop 0
	global_load_dwordx4 v[64:67], v64, s[26:27]
	s_nop 0
	global_load_dwordx4 v[40:43], v[144:145], off
	ds_read_b128 v[140:143], v185 offset:256
	ds_read_b128 v[136:139], v185 offset:272
	s_mov_b32 s76, 0
	s_branch .LBB0_1379
